# hand-written row passes (LDS-staged params, all loads in flight, DPP reductions) + mlaproj rstd loads batched 8-deep + MLA loop trims
# speedup vs baseline: 1.0206x; 1.0206x over previous
.LBB0_88:
	s_andn2_b64 vcc, exec, s[4:5]
	s_cbranch_vccnz .LBB0_475
	s_add_i32 s0, s88, -2
	s_mul_hi_i32 s1, s0, 0x66666667
	s_lshr_b32 s2, s1, 31
	s_ashr_i32 s1, s1, 2
	s_add_i32 s4, s1, s2
	s_mul_i32 s1, s4, 10
	s_sub_i32 s9, s0, s1
	s_add_i32 s0, s88, 7
	s_cmp_lt_u32 s0, 19
	s_cselect_b64 s[6:7], -1, 0
	v_writelane_b32 v225, s14, 50
	s_and_b64 s[0:1], s[6:7], exec
	s_movk_i32 s0, 0x108
	v_writelane_b32 v225, s15, 51
	s_cselect_b32 s22, s0, 0x100
	s_ashr_i32 s5, s4, 31
	s_mul_i32 s8, s4, 0x22a0000
	v_readlane_b32 s0, v225, 48
	s_mul_hi_i32 s2, s4, 0x22a0000
	v_readlane_b32 s1, v225, 49
	v_writelane_b32 v225, s8, 52
	s_add_u32 s59, s0, s8
	v_writelane_b32 v225, s2, 53
	s_addc_u32 s0, s1, s2
	v_writelane_b32 v225, s0, 54
	v_writelane_b32 v225, s9, 55
	s_cmp_lt_i32 s9, 5
	s_mov_b64 s[0:1], -1
	v_writelane_b32 v225, s88, 56
	s_cbranch_scc1 .LBB0_183
	v_readlane_b32 s0, v225, 50
	v_readlane_b32 s1, v225, 51
	s_lshl_b64 s[0:1], s[0:1], 2
	v_readlane_b32 s8, v226, 1
	v_readlane_b32 s9, v226, 2
	s_add_u32 s8, s8, s0
	s_addc_u32 s9, s9, s1
	v_readlane_b32 s0, v225, 55
	s_cmp_lt_i32 s0, 7
	s_mov_b64 s[0:1], -1
	v_readlane_b32 s10, v226, 3
	v_readlane_b32 s11, v226, 4
	s_cbranch_scc1 .LBB0_155
	v_readlane_b32 s0, v225, 55
	s_cmp_lt_i32 s0, 8
	s_mov_b64 s[0:1], -1
	s_cbranch_scc1 .LBB0_129
	v_readlane_b32 s0, v225, 55
	s_cmp_lt_i32 s0, 9
	s_mov_b64 s[0:1], -1
	s_cbranch_scc1 .LBB0_115
	v_readlane_b32 s0, v225, 55
	s_cmp_eq_u32 s0, 9
	s_cbranch_scc0 .LBB0_114
	s_lshl_b32 s2, s22, 3
	v_readlane_b32 s0, v226, 0
	v_mov_b32_e32 v0, v196
	s_cmp_ge_i32 s0, s2
	s_cbranch_scc1 .LBB0_114
	v_writelane_b32 v224, s59, 17
	v_readlane_b32 s14, v225, 48
	v_readlane_b32 s15, v225, 49
	s_add_u32 s10, s14, 0x457c000
	s_addc_u32 s11, s15, 0
	s_add_u32 s12, s14, 0x497c000
	s_addc_u32 s13, s15, 0
	s_add_u32 s0, s14, 0x4540000
	s_addc_u32 s1, s15, 0
	s_add_u32 s14, s14, 0x1871c000
	s_addc_u32 s15, s15, 0
	s_mov_b32 s16, s8
	s_mov_b32 s17, s9
	s_mov_b32 s18, s10
	s_mov_b32 s19, s11
	s_mul_i32 s45, s4, 0x1e000
	s_add_u32 s0, s0, s45
	s_addc_u32 s1, s1, 0
	s_add_u32 s24, s0, 0x5000
	s_addc_u32 s25, s1, 0
	s_add_u32 s38, s0, 0x1e000
	s_addc_u32 s39, s1, 0
	s_add_u32 s46, s0, 0x1f000
	s_addc_u32 s47, s1, 0
	s_lshl_b32 s45, s4, 12
	v_readlane_b32 s26, v225, 12
	v_readlane_b32 s27, v225, 13
	s_add_u32 s26, s26, s45
	s_addc_u32 s27, s27, 0
	s_add_u32 s40, s72, s45
	s_addc_u32 s41, s73, 0
	s_add_u32 s40, s40, 0x1000
	s_addc_u32 s41, s41, 0
	s_cmp_eq_u32 s4, 0
	s_cselect_b32 s43, 1, 0
	s_mov_b32 s44, 1
	s_branch .Lrows_fill

.LBB0_155:
	s_andn2_b64 vcc, exec, s[0:1]
	s_cbranch_vccnz .LBB0_182
	v_readlane_b32 s0, v225, 55
	s_cmp_gt_i32 s0, 5
	s_mov_b64 s[0:1], -1
	s_cbranch_scc0 .LBB0_169
	s_lshl_b32 s2, s22, 3
	v_readlane_b32 s0, v226, 0
	s_mov_b32 s54, s59
	s_mov_b64 s[52:53], s[94:95]
	s_mov_b64 s[82:83], 0x3000
	v_mov_b32_e32 v0, v196
	s_cmp_ge_i32 s0, s2
	s_mov_b64 s[94:95], 0x1800
	s_cbranch_scc1 .LBB0_168
	v_readlane_b32 s14, v225, 48
	v_readlane_b32 s15, v225, 49
	s_add_u32 s10, s14, 0x457c000
	s_addc_u32 s11, s15, 0
	s_add_u32 s12, s14, 0x497c000
	s_addc_u32 s13, s15, 0
	s_add_u32 s0, s14, 0x4540000
	s_addc_u32 s1, s15, 0
	s_add_u32 s14, s14, 0x1871c000
	s_addc_u32 s15, s15, 0
	s_and_b64 s[16:17], s[6:7], exec
	s_cselect_b32 s17, s61, s9
	s_cselect_b32 s16, s60, s8
	s_cselect_b32 s19, s65, s11
	s_cselect_b32 s18, s64, s10
	s_mul_i32 s45, s4, 0x1e000
	s_add_u32 s0, s0, s45
	s_addc_u32 s1, s1, 0
	s_add_u32 s24, s0, 0x2000
	s_addc_u32 s25, s1, 0
	s_add_u32 s38, s0, 0x3000
	s_addc_u32 s39, s1, 0
	s_add_u32 s46, s0, 0x4000
	s_addc_u32 s47, s1, 0
	s_lshl_b32 s45, s4, 12
	s_add_u32 s26, s74, s45
	s_addc_u32 s27, s75, 0
	v_readlane_b32 s40, v225, 10
	v_readlane_b32 s41, v225, 11
	s_add_u32 s40, s40, s45
	s_addc_u32 s41, s41, 0
	s_mov_b32 s43, 1
	s_mov_b32 s44, 0
.Lrows_fill:
	v_lshlrev_b32_e32 v3, 4, v196
	global_load_dwordx4 v[10:13], v3, s[24:25]
	s_add_u32 s24, s24, 0x6000
	s_addc_u32 s25, s25, 0
	global_load_dwordx4 v[14:17], v3, s[24:25]
	s_add_u32 s24, s24, 0x6000
	s_addc_u32 s25, s25, 0
	global_load_dwordx4 v[18:21], v3, s[24:25]
	s_add_u32 s24, s24, 0x6000
	s_addc_u32 s25, s25, 0
	global_load_dwordx4 v[22:25], v3, s[24:25]
	s_add_u32 s24, s24, 0x6000
	s_addc_u32 s25, s25, 0
	global_load_dwordx4 v[26:29], v3, s[24:25]
	global_load_dwordx4 v[30:33], v3, s[26:27]
	s_cmp_eq_u32 s43, 0
	s_cbranch_scc1 .Lrows_fill_w
	global_load_dwordx4 v[34:37], v3, s[38:39]
	global_load_dwordx4 v[54:57], v3, s[46:47]
	s_add_u32 s38, s38, 0x6000
	s_addc_u32 s39, s39, 0
	s_add_u32 s46, s46, 0x6000
	s_addc_u32 s47, s47, 0
	global_load_dwordx4 v[38:41], v3, s[38:39]
	global_load_dwordx4 v[58:61], v3, s[46:47]
	s_add_u32 s38, s38, 0x6000
	s_addc_u32 s39, s39, 0
	s_add_u32 s46, s46, 0x6000
	s_addc_u32 s47, s47, 0
	global_load_dwordx4 v[42:45], v3, s[38:39]
	global_load_dwordx4 v[62:65], v3, s[46:47]
	s_add_u32 s38, s38, 0x6000
	s_addc_u32 s39, s39, 0
	s_add_u32 s46, s46, 0x6000
	s_addc_u32 s47, s47, 0
	global_load_dwordx4 v[46:49], v3, s[38:39]
	global_load_dwordx4 v[66:69], v3, s[46:47]
	s_add_u32 s38, s38, 0x6000
	s_addc_u32 s39, s39, 0
	s_add_u32 s46, s46, 0x6000
	s_addc_u32 s47, s47, 0
	global_load_dwordx4 v[50:53], v3, s[38:39]
	global_load_dwordx4 v[70:73], v3, s[46:47]
	global_load_dwordx4 v[74:77], v3, s[40:41]
.Lrows_fill_w:
	s_waitcnt vmcnt(0)
	ds_write_b128 v3, v[10:13] offset:0
	ds_write_b128 v3, v[14:17] offset:4096
	ds_write_b128 v3, v[18:21] offset:8192
	ds_write_b128 v3, v[22:25] offset:12288
	ds_write_b128 v3, v[26:29] offset:16384
	ds_write_b128 v3, v[30:33] offset:61440
	s_cmp_eq_u32 s43, 0
	s_cbranch_scc1 .Lrows_fill_d
	ds_write_b128 v3, v[34:37] offset:20480
	ds_write_b128 v3, v[54:57] offset:40960
	ds_write_b128 v3, v[38:41] offset:24576
	ds_write_b128 v3, v[58:61] offset:45056
	ds_write_b128 v3, v[42:45] offset:28672
	ds_write_b128 v3, v[62:65] offset:49152
	ds_write_b128 v3, v[46:49] offset:32768
	ds_write_b128 v3, v[66:69] offset:53248
	ds_write_b128 v3, v[50:53] offset:36864
	ds_write_b128 v3, v[70:73] offset:57344
	v_add_u32_e32 v5, 0x10000, v3
	ds_write_b128 v5, v[74:77]
.Lrows_fill_d:
	s_waitcnt lgkmcnt(0)
	s_barrier
	v_and_b32_e32 v4, 63, v196
	v_lshlrev_b32_e32 v3, 4, v4
	v_lshlrev_b32_e32 v4, 3, v4
	v_add_u32_e32 v6, 0xf000, v3
	v_readfirstlane_b32 s23, v196
	s_nop 3
	s_lshr_b32 s23, s23, 6
	s_lshl_b32 s23, s23, 2
	v_readlane_b32 s20, v226, 0
	v_readlane_b32 s0, v225, 42
	v_readlane_b32 s1, v225, 43
	s_load_dword s21, s[0:1], 0x0
	s_waitcnt lgkmcnt(0)
.Lrows_item:
	s_lshl_b32 s45, s20, 4
	s_add_i32 s45, s45, s23
	s_cmp_ge_u32 s45, 0x8000
	s_cbranch_scc1 .Lrows_ctx
	s_lshr_b32 s46, s45, 13
	s_lshl_b32 s0, s45, 12
	s_add_u32 s24, s16, s0
	s_addc_u32 s25, s17, 0
	s_add_u32 s26, s8, s0
	s_addc_u32 s27, s9, 0
	s_branch .Lrows_common
.Lrows_ctx:
	s_sub_u32 s47, s45, 0x8000
	s_mov_b32 s46, 4
	s_lshl_b32 s0, s47, 12
	s_add_u32 s24, s18, s0
	s_addc_u32 s25, s19, 0
	s_add_u32 s26, s10, s0
	s_addc_u32 s27, s11, 0
.Lrows_common:
	s_lshl_b32 s0, s45, 11
	s_add_u32 s38, s14, s0
	s_addc_u32 s39, s15, 0
	s_add_u32 s40, s12, s0
	s_addc_u32 s41, s13, 0
	s_lshl_b32 s42, s46, 12
	v_add_u32_e32 v5, s42, v3
	global_load_dwordx2 v[74:75], v4, s[38:39]
	global_load_dwordx2 v[76:77], v4, s[38:39] offset:512
	global_load_dwordx2 v[78:79], v4, s[38:39] offset:1024
	global_load_dwordx2 v[80:81], v4, s[38:39] offset:1536
	s_add_u32 s38, s38, 0x800
	s_addc_u32 s39, s39, 0
	global_load_dwordx2 v[82:83], v4, s[38:39]
	global_load_dwordx2 v[84:85], v4, s[38:39] offset:512
	global_load_dwordx2 v[86:87], v4, s[38:39] offset:1024
	global_load_dwordx2 v[88:89], v4, s[38:39] offset:1536
	s_add_u32 s38, s38, 0x800
	s_addc_u32 s39, s39, 0
	global_load_dwordx2 v[90:91], v4, s[38:39]
	global_load_dwordx2 v[92:93], v4, s[38:39] offset:512
	global_load_dwordx2 v[94:95], v4, s[38:39] offset:1024
	global_load_dwordx2 v[96:97], v4, s[38:39] offset:1536
	s_add_u32 s38, s38, 0x800
	s_addc_u32 s39, s39, 0
	global_load_dwordx2 v[98:99], v4, s[38:39]
	global_load_dwordx2 v[100:101], v4, s[38:39] offset:512
	global_load_dwordx2 v[102:103], v4, s[38:39] offset:1024
	global_load_dwordx2 v[104:105], v4, s[38:39] offset:1536
	global_load_dwordx4 v[10:13], v3, s[24:25]
	global_load_dwordx4 v[14:17], v3, s[24:25] offset:1024
	global_load_dwordx4 v[18:21], v3, s[24:25] offset:2048
	global_load_dwordx4 v[22:25], v3, s[24:25] offset:3072
	s_add_u32 s24, s24, 0x1000
	s_addc_u32 s25, s25, 0
	global_load_dwordx4 v[26:29], v3, s[24:25]
	global_load_dwordx4 v[30:33], v3, s[24:25] offset:1024
	global_load_dwordx4 v[34:37], v3, s[24:25] offset:2048
	global_load_dwordx4 v[38:41], v3, s[24:25] offset:3072
	s_add_u32 s24, s24, 0x1000
	s_addc_u32 s25, s25, 0
	global_load_dwordx4 v[42:45], v3, s[24:25]
	global_load_dwordx4 v[46:49], v3, s[24:25] offset:1024
	global_load_dwordx4 v[50:53], v3, s[24:25] offset:2048
	global_load_dwordx4 v[54:57], v3, s[24:25] offset:3072
	s_add_u32 s24, s24, 0x1000
	s_addc_u32 s25, s25, 0
	global_load_dwordx4 v[58:61], v3, s[24:25]
	global_load_dwordx4 v[62:65], v3, s[24:25] offset:1024
	global_load_dwordx4 v[66:69], v3, s[24:25] offset:2048
	global_load_dwordx4 v[70:73], v3, s[24:25] offset:3072
	s_waitcnt vmcnt(16)
	v_lshlrev_b32_e32 v122, 16, v74
	v_and_b32_e32 v123, 0xffff0000, v74
	v_lshlrev_b32_e32 v124, 16, v82
	v_and_b32_e32 v125, 0xffff0000, v82
	v_lshlrev_b32_e32 v126, 16, v90
	v_and_b32_e32 v127, 0xffff0000, v90
	v_lshlrev_b32_e32 v128, 16, v98
	v_and_b32_e32 v129, 0xffff0000, v98
	v_pk_mul_f32 v[132:133], v[122:123], v[122:123]
	v_pk_mul_f32 v[134:135], v[124:125], v[124:125]
	v_pk_mul_f32 v[136:137], v[126:127], v[126:127]
	v_pk_mul_f32 v[138:139], v[128:129], v[128:129]
	v_add_f32_e32 v106, v132, v133
	v_add_f32_e32 v107, v134, v135
	v_add_f32_e32 v108, v136, v137
	v_add_f32_e32 v109, v138, v139
	v_lshlrev_b32_e32 v122, 16, v75
	v_and_b32_e32 v123, 0xffff0000, v75
	v_lshlrev_b32_e32 v124, 16, v83
	v_and_b32_e32 v125, 0xffff0000, v83
	v_lshlrev_b32_e32 v126, 16, v91
	v_and_b32_e32 v127, 0xffff0000, v91
	v_lshlrev_b32_e32 v128, 16, v99
	v_and_b32_e32 v129, 0xffff0000, v99
	v_pk_mul_f32 v[132:133], v[122:123], v[122:123]
	v_pk_mul_f32 v[134:135], v[124:125], v[124:125]
	v_pk_mul_f32 v[136:137], v[126:127], v[126:127]
	v_pk_mul_f32 v[138:139], v[128:129], v[128:129]
	v_add_f32_e32 v106, v106, v132
	v_add_f32_e32 v107, v107, v134
	v_add_f32_e32 v108, v108, v136
	v_add_f32_e32 v109, v109, v138
	v_add_f32_e32 v106, v133, v106
	v_add_f32_e32 v107, v135, v107
	v_add_f32_e32 v108, v137, v108
	v_add_f32_e32 v109, v139, v109
	v_lshlrev_b32_e32 v122, 16, v76
	v_and_b32_e32 v123, 0xffff0000, v76
	v_lshlrev_b32_e32 v124, 16, v84
	v_and_b32_e32 v125, 0xffff0000, v84
	v_lshlrev_b32_e32 v126, 16, v92
	v_and_b32_e32 v127, 0xffff0000, v92
	v_lshlrev_b32_e32 v128, 16, v100
	v_and_b32_e32 v129, 0xffff0000, v100
	v_pk_mul_f32 v[132:133], v[122:123], v[122:123]
	v_pk_mul_f32 v[134:135], v[124:125], v[124:125]
	v_pk_mul_f32 v[136:137], v[126:127], v[126:127]
	v_pk_mul_f32 v[138:139], v[128:129], v[128:129]
	v_add_f32_e32 v106, v106, v132
	v_add_f32_e32 v107, v107, v134
	v_add_f32_e32 v108, v108, v136
	v_add_f32_e32 v109, v109, v138
	v_add_f32_e32 v106, v133, v106
	v_add_f32_e32 v107, v135, v107
	v_add_f32_e32 v108, v137, v108
	v_add_f32_e32 v109, v139, v109
	v_lshlrev_b32_e32 v122, 16, v77
	v_and_b32_e32 v123, 0xffff0000, v77
	v_lshlrev_b32_e32 v124, 16, v85
	v_and_b32_e32 v125, 0xffff0000, v85
	v_lshlrev_b32_e32 v126, 16, v93
	v_and_b32_e32 v127, 0xffff0000, v93
	v_lshlrev_b32_e32 v128, 16, v101
	v_and_b32_e32 v129, 0xffff0000, v101
	v_pk_mul_f32 v[132:133], v[122:123], v[122:123]
	v_pk_mul_f32 v[134:135], v[124:125], v[124:125]
	v_pk_mul_f32 v[136:137], v[126:127], v[126:127]
	v_pk_mul_f32 v[138:139], v[128:129], v[128:129]
	v_add_f32_e32 v106, v106, v132
	v_add_f32_e32 v107, v107, v134
	v_add_f32_e32 v108, v108, v136
	v_add_f32_e32 v109, v109, v138
	v_add_f32_e32 v106, v133, v106
	v_add_f32_e32 v107, v135, v107
	v_add_f32_e32 v108, v137, v108
	v_add_f32_e32 v109, v139, v109
	v_lshlrev_b32_e32 v122, 16, v78
	v_and_b32_e32 v123, 0xffff0000, v78
	v_lshlrev_b32_e32 v124, 16, v86
	v_and_b32_e32 v125, 0xffff0000, v86
	v_lshlrev_b32_e32 v126, 16, v94
	v_and_b32_e32 v127, 0xffff0000, v94
	v_lshlrev_b32_e32 v128, 16, v102
	v_and_b32_e32 v129, 0xffff0000, v102
	v_pk_mul_f32 v[132:133], v[122:123], v[122:123]
	v_pk_mul_f32 v[134:135], v[124:125], v[124:125]
	v_pk_mul_f32 v[136:137], v[126:127], v[126:127]
	v_pk_mul_f32 v[138:139], v[128:129], v[128:129]
	v_add_f32_e32 v106, v106, v132
	v_add_f32_e32 v107, v107, v134
	v_add_f32_e32 v108, v108, v136
	v_add_f32_e32 v109, v109, v138
	v_add_f32_e32 v106, v133, v106
	v_add_f32_e32 v107, v135, v107
	v_add_f32_e32 v108, v137, v108
	v_add_f32_e32 v109, v139, v109
	v_lshlrev_b32_e32 v122, 16, v79
	v_and_b32_e32 v123, 0xffff0000, v79
	v_lshlrev_b32_e32 v124, 16, v87
	v_and_b32_e32 v125, 0xffff0000, v87
	v_lshlrev_b32_e32 v126, 16, v95
	v_and_b32_e32 v127, 0xffff0000, v95
	v_lshlrev_b32_e32 v128, 16, v103
	v_and_b32_e32 v129, 0xffff0000, v103
	v_pk_mul_f32 v[132:133], v[122:123], v[122:123]
	v_pk_mul_f32 v[134:135], v[124:125], v[124:125]
	v_pk_mul_f32 v[136:137], v[126:127], v[126:127]
	v_pk_mul_f32 v[138:139], v[128:129], v[128:129]
	v_add_f32_e32 v106, v106, v132
	v_add_f32_e32 v107, v107, v134
	v_add_f32_e32 v108, v108, v136
	v_add_f32_e32 v109, v109, v138
	v_add_f32_e32 v106, v133, v106
	v_add_f32_e32 v107, v135, v107
	v_add_f32_e32 v108, v137, v108
	v_add_f32_e32 v109, v139, v109
	v_lshlrev_b32_e32 v122, 16, v80
	v_and_b32_e32 v123, 0xffff0000, v80
	v_lshlrev_b32_e32 v124, 16, v88
	v_and_b32_e32 v125, 0xffff0000, v88
	v_lshlrev_b32_e32 v126, 16, v96
	v_and_b32_e32 v127, 0xffff0000, v96
	v_lshlrev_b32_e32 v128, 16, v104
	v_and_b32_e32 v129, 0xffff0000, v104
	v_pk_mul_f32 v[132:133], v[122:123], v[122:123]
	v_pk_mul_f32 v[134:135], v[124:125], v[124:125]
	v_pk_mul_f32 v[136:137], v[126:127], v[126:127]
	v_pk_mul_f32 v[138:139], v[128:129], v[128:129]
	v_add_f32_e32 v106, v106, v132
	v_add_f32_e32 v107, v107, v134
	v_add_f32_e32 v108, v108, v136
	v_add_f32_e32 v109, v109, v138
	v_add_f32_e32 v106, v133, v106
	v_add_f32_e32 v107, v135, v107
	v_add_f32_e32 v108, v137, v108
	v_add_f32_e32 v109, v139, v109
	v_lshlrev_b32_e32 v122, 16, v81
	v_and_b32_e32 v123, 0xffff0000, v81
	v_lshlrev_b32_e32 v124, 16, v89
	v_and_b32_e32 v125, 0xffff0000, v89
	v_lshlrev_b32_e32 v126, 16, v97
	v_and_b32_e32 v127, 0xffff0000, v97
	v_lshlrev_b32_e32 v128, 16, v105
	v_and_b32_e32 v129, 0xffff0000, v105
	v_pk_mul_f32 v[132:133], v[122:123], v[122:123]
	v_pk_mul_f32 v[134:135], v[124:125], v[124:125]
	v_pk_mul_f32 v[136:137], v[126:127], v[126:127]
	v_pk_mul_f32 v[138:139], v[128:129], v[128:129]
	v_add_f32_e32 v106, v106, v132
	v_add_f32_e32 v107, v107, v134
	v_add_f32_e32 v108, v108, v136
	v_add_f32_e32 v109, v109, v138
	v_add_f32_e32 v106, v133, v106
	v_add_f32_e32 v107, v135, v107
	v_add_f32_e32 v108, v137, v108
	v_add_f32_e32 v109, v139, v109
	v_mov_b32_e32 v110, v106
	v_mov_b32_e32 v111, v107
	v_mov_b32_e32 v112, v108
	v_mov_b32_e32 v113, v109
	v_permlane32_swap_b32_e32 v106, v110
	v_permlane32_swap_b32_e32 v107, v111
	v_permlane32_swap_b32_e32 v108, v112
	v_permlane32_swap_b32_e32 v109, v113
	v_add_f32_e32 v106, v106, v110
	v_add_f32_e32 v107, v107, v111
	v_add_f32_e32 v108, v108, v112
	v_add_f32_e32 v109, v109, v113
	v_mov_b32_e32 v110, v106
	v_mov_b32_e32 v111, v107
	v_mov_b32_e32 v112, v108
	v_mov_b32_e32 v113, v109
	v_permlane16_swap_b32_e32 v106, v110
	v_permlane16_swap_b32_e32 v107, v111
	v_permlane16_swap_b32_e32 v108, v112
	v_permlane16_swap_b32_e32 v109, v113
	v_add_f32_e32 v106, v106, v110
	v_add_f32_e32 v107, v107, v111
	v_add_f32_e32 v108, v108, v112
	v_add_f32_e32 v109, v109, v113
	v_add_f32_dpp v106, v106, v106 row_ror:8 row_mask:0xf bank_mask:0xf
	v_add_f32_dpp v107, v107, v107 row_ror:8 row_mask:0xf bank_mask:0xf
	v_add_f32_dpp v108, v108, v108 row_ror:8 row_mask:0xf bank_mask:0xf
	v_add_f32_dpp v109, v109, v109 row_ror:8 row_mask:0xf bank_mask:0xf
	v_add_f32_dpp v110, v106, v106 row_shl:4 row_mask:0xf bank_mask:0x5
	v_add_f32_dpp v111, v107, v107 row_shl:4 row_mask:0xf bank_mask:0x5
	v_add_f32_dpp v112, v108, v108 row_shl:4 row_mask:0xf bank_mask:0x5
	v_add_f32_dpp v113, v109, v109 row_shl:4 row_mask:0xf bank_mask:0x5
	v_add_f32_dpp v110, v106, v106 row_shr:4 row_mask:0xf bank_mask:0xa
	v_add_f32_dpp v111, v107, v107 row_shr:4 row_mask:0xf bank_mask:0xa
	v_add_f32_dpp v112, v108, v108 row_shr:4 row_mask:0xf bank_mask:0xa
	v_add_f32_dpp v113, v109, v109 row_shr:4 row_mask:0xf bank_mask:0xa
	v_add_f32_dpp v106, v110, v110 quad_perm:[2,3,0,1] row_mask:0xf bank_mask:0xf
	v_add_f32_dpp v107, v111, v111 quad_perm:[2,3,0,1] row_mask:0xf bank_mask:0xf
	v_add_f32_dpp v108, v112, v112 quad_perm:[2,3,0,1] row_mask:0xf bank_mask:0xf
	v_add_f32_dpp v109, v113, v113 quad_perm:[2,3,0,1] row_mask:0xf bank_mask:0xf
	v_add_f32_dpp v110, v106, v106 quad_perm:[1,0,3,2] row_mask:0xf bank_mask:0xf
	v_add_f32_dpp v111, v107, v107 quad_perm:[1,0,3,2] row_mask:0xf bank_mask:0xf
	v_add_f32_dpp v112, v108, v108 quad_perm:[1,0,3,2] row_mask:0xf bank_mask:0xf
	v_add_f32_dpp v113, v109, v109 quad_perm:[1,0,3,2] row_mask:0xf bank_mask:0xf
	v_fmamk_f32 v110, v110, 0x3a800000, v198
	v_fmamk_f32 v111, v111, 0x3a800000, v198
	v_fmamk_f32 v112, v112, 0x3a800000, v198
	v_fmamk_f32 v113, v113, 0x3a800000, v198
	v_rsq_f32_e32 v114, v110
	v_rsq_f32_e32 v116, v111
	v_rsq_f32_e32 v118, v112
	v_rsq_f32_e32 v120, v113
	ds_read_b128 v[140:143], v5 offset:0
	ds_read_b128 v[144:147], v6 offset:0
	s_waitcnt vmcnt(12)
	v_lshlrev_b32_e32 v122, 16, v74
	v_and_b32_e32 v123, 0xffff0000, v74
	v_lshlrev_b32_e32 v124, 16, v75
	v_and_b32_e32 v125, 0xffff0000, v75
	s_waitcnt lgkmcnt(0)
	v_pk_mul_f32 v[122:123], v[114:115], v[122:123] op_sel_hi:[0,1]
	v_pk_mul_f32 v[124:125], v[114:115], v[124:125] op_sel_hi:[0,1]
	v_pk_mul_f32 v[122:123], v[144:145], v[122:123]
	v_pk_mul_f32 v[124:125], v[146:147], v[124:125]
	v_pk_fma_f32 v[10:11], v[140:141], v[122:123], v[10:11]
	v_pk_fma_f32 v[12:13], v[142:143], v[124:125], v[12:13]
	s_waitcnt vmcnt(8)
	v_lshlrev_b32_e32 v122, 16, v82
	v_and_b32_e32 v123, 0xffff0000, v82
	v_lshlrev_b32_e32 v124, 16, v83
	v_and_b32_e32 v125, 0xffff0000, v83
	v_pk_mul_f32 v[122:123], v[116:117], v[122:123] op_sel_hi:[0,1]
	v_pk_mul_f32 v[124:125], v[116:117], v[124:125] op_sel_hi:[0,1]
	v_pk_mul_f32 v[122:123], v[144:145], v[122:123]
	v_pk_mul_f32 v[124:125], v[146:147], v[124:125]
	v_pk_fma_f32 v[26:27], v[140:141], v[122:123], v[26:27]
	v_pk_fma_f32 v[28:29], v[142:143], v[124:125], v[28:29]
	s_waitcnt vmcnt(4)
	v_lshlrev_b32_e32 v122, 16, v90
	v_and_b32_e32 v123, 0xffff0000, v90
	v_lshlrev_b32_e32 v124, 16, v91
	v_and_b32_e32 v125, 0xffff0000, v91
	v_pk_mul_f32 v[122:123], v[118:119], v[122:123] op_sel_hi:[0,1]
	v_pk_mul_f32 v[124:125], v[118:119], v[124:125] op_sel_hi:[0,1]
	v_pk_mul_f32 v[122:123], v[144:145], v[122:123]
	v_pk_mul_f32 v[124:125], v[146:147], v[124:125]
	v_pk_fma_f32 v[42:43], v[140:141], v[122:123], v[42:43]
	v_pk_fma_f32 v[44:45], v[142:143], v[124:125], v[44:45]
	s_waitcnt vmcnt(0)
	v_lshlrev_b32_e32 v122, 16, v98
	v_and_b32_e32 v123, 0xffff0000, v98
	v_lshlrev_b32_e32 v124, 16, v99
	v_and_b32_e32 v125, 0xffff0000, v99
	v_pk_mul_f32 v[122:123], v[120:121], v[122:123] op_sel_hi:[0,1]
	v_pk_mul_f32 v[124:125], v[120:121], v[124:125] op_sel_hi:[0,1]
	v_pk_mul_f32 v[122:123], v[144:145], v[122:123]
	v_pk_mul_f32 v[124:125], v[146:147], v[124:125]
	v_pk_fma_f32 v[58:59], v[140:141], v[122:123], v[58:59]
	v_pk_fma_f32 v[60:61], v[142:143], v[124:125], v[60:61]
	ds_read_b128 v[140:143], v5 offset:1024
	ds_read_b128 v[144:147], v6 offset:1024
	v_lshlrev_b32_e32 v122, 16, v76
	v_and_b32_e32 v123, 0xffff0000, v76
	v_lshlrev_b32_e32 v124, 16, v77
	v_and_b32_e32 v125, 0xffff0000, v77
	s_waitcnt lgkmcnt(0)
	v_pk_mul_f32 v[122:123], v[114:115], v[122:123] op_sel_hi:[0,1]
	v_pk_mul_f32 v[124:125], v[114:115], v[124:125] op_sel_hi:[0,1]
	v_pk_mul_f32 v[122:123], v[144:145], v[122:123]
	v_pk_mul_f32 v[124:125], v[146:147], v[124:125]
	v_pk_fma_f32 v[14:15], v[140:141], v[122:123], v[14:15]
	v_pk_fma_f32 v[16:17], v[142:143], v[124:125], v[16:17]
	v_lshlrev_b32_e32 v122, 16, v84
	v_and_b32_e32 v123, 0xffff0000, v84
	v_lshlrev_b32_e32 v124, 16, v85
	v_and_b32_e32 v125, 0xffff0000, v85
	v_pk_mul_f32 v[122:123], v[116:117], v[122:123] op_sel_hi:[0,1]
	v_pk_mul_f32 v[124:125], v[116:117], v[124:125] op_sel_hi:[0,1]
	v_pk_mul_f32 v[122:123], v[144:145], v[122:123]
	v_pk_mul_f32 v[124:125], v[146:147], v[124:125]
	v_pk_fma_f32 v[30:31], v[140:141], v[122:123], v[30:31]
	v_pk_fma_f32 v[32:33], v[142:143], v[124:125], v[32:33]
	v_lshlrev_b32_e32 v122, 16, v92
	v_and_b32_e32 v123, 0xffff0000, v92
	v_lshlrev_b32_e32 v124, 16, v93
	v_and_b32_e32 v125, 0xffff0000, v93
	v_pk_mul_f32 v[122:123], v[118:119], v[122:123] op_sel_hi:[0,1]
	v_pk_mul_f32 v[124:125], v[118:119], v[124:125] op_sel_hi:[0,1]
	v_pk_mul_f32 v[122:123], v[144:145], v[122:123]
	v_pk_mul_f32 v[124:125], v[146:147], v[124:125]
	v_pk_fma_f32 v[46:47], v[140:141], v[122:123], v[46:47]
	v_pk_fma_f32 v[48:49], v[142:143], v[124:125], v[48:49]
	v_lshlrev_b32_e32 v122, 16, v100
	v_and_b32_e32 v123, 0xffff0000, v100
	v_lshlrev_b32_e32 v124, 16, v101
	v_and_b32_e32 v125, 0xffff0000, v101
	v_pk_mul_f32 v[122:123], v[120:121], v[122:123] op_sel_hi:[0,1]
	v_pk_mul_f32 v[124:125], v[120:121], v[124:125] op_sel_hi:[0,1]
	v_pk_mul_f32 v[122:123], v[144:145], v[122:123]
	v_pk_mul_f32 v[124:125], v[146:147], v[124:125]
	v_pk_fma_f32 v[62:63], v[140:141], v[122:123], v[62:63]
	v_pk_fma_f32 v[64:65], v[142:143], v[124:125], v[64:65]
	ds_read_b128 v[140:143], v5 offset:2048
	ds_read_b128 v[144:147], v6 offset:2048
	v_lshlrev_b32_e32 v122, 16, v78
	v_and_b32_e32 v123, 0xffff0000, v78
	v_lshlrev_b32_e32 v124, 16, v79
	v_and_b32_e32 v125, 0xffff0000, v79
	s_waitcnt lgkmcnt(0)
	v_pk_mul_f32 v[122:123], v[114:115], v[122:123] op_sel_hi:[0,1]
	v_pk_mul_f32 v[124:125], v[114:115], v[124:125] op_sel_hi:[0,1]
	v_pk_mul_f32 v[122:123], v[144:145], v[122:123]
	v_pk_mul_f32 v[124:125], v[146:147], v[124:125]
	v_pk_fma_f32 v[18:19], v[140:141], v[122:123], v[18:19]
	v_pk_fma_f32 v[20:21], v[142:143], v[124:125], v[20:21]
	v_lshlrev_b32_e32 v122, 16, v86
	v_and_b32_e32 v123, 0xffff0000, v86
	v_lshlrev_b32_e32 v124, 16, v87
	v_and_b32_e32 v125, 0xffff0000, v87
	v_pk_mul_f32 v[122:123], v[116:117], v[122:123] op_sel_hi:[0,1]
	v_pk_mul_f32 v[124:125], v[116:117], v[124:125] op_sel_hi:[0,1]
	v_pk_mul_f32 v[122:123], v[144:145], v[122:123]
	v_pk_mul_f32 v[124:125], v[146:147], v[124:125]
	v_pk_fma_f32 v[34:35], v[140:141], v[122:123], v[34:35]
	v_pk_fma_f32 v[36:37], v[142:143], v[124:125], v[36:37]
	v_lshlrev_b32_e32 v122, 16, v94
	v_and_b32_e32 v123, 0xffff0000, v94
	v_lshlrev_b32_e32 v124, 16, v95
	v_and_b32_e32 v125, 0xffff0000, v95
	v_pk_mul_f32 v[122:123], v[118:119], v[122:123] op_sel_hi:[0,1]
	v_pk_mul_f32 v[124:125], v[118:119], v[124:125] op_sel_hi:[0,1]
	v_pk_mul_f32 v[122:123], v[144:145], v[122:123]
	v_pk_mul_f32 v[124:125], v[146:147], v[124:125]
	v_pk_fma_f32 v[50:51], v[140:141], v[122:123], v[50:51]
	v_pk_fma_f32 v[52:53], v[142:143], v[124:125], v[52:53]
	v_lshlrev_b32_e32 v122, 16, v102
	v_and_b32_e32 v123, 0xffff0000, v102
	v_lshlrev_b32_e32 v124, 16, v103
	v_and_b32_e32 v125, 0xffff0000, v103
	v_pk_mul_f32 v[122:123], v[120:121], v[122:123] op_sel_hi:[0,1]
	v_pk_mul_f32 v[124:125], v[120:121], v[124:125] op_sel_hi:[0,1]
	v_pk_mul_f32 v[122:123], v[144:145], v[122:123]
	v_pk_mul_f32 v[124:125], v[146:147], v[124:125]
	v_pk_fma_f32 v[66:67], v[140:141], v[122:123], v[66:67]
	v_pk_fma_f32 v[68:69], v[142:143], v[124:125], v[68:69]
	ds_read_b128 v[140:143], v5 offset:3072
	ds_read_b128 v[144:147], v6 offset:3072
	v_lshlrev_b32_e32 v122, 16, v80
	v_and_b32_e32 v123, 0xffff0000, v80
	v_lshlrev_b32_e32 v124, 16, v81
	v_and_b32_e32 v125, 0xffff0000, v81
	s_waitcnt lgkmcnt(0)
	v_pk_mul_f32 v[122:123], v[114:115], v[122:123] op_sel_hi:[0,1]
	v_pk_mul_f32 v[124:125], v[114:115], v[124:125] op_sel_hi:[0,1]
	v_pk_mul_f32 v[122:123], v[144:145], v[122:123]
	v_pk_mul_f32 v[124:125], v[146:147], v[124:125]
	v_pk_fma_f32 v[22:23], v[140:141], v[122:123], v[22:23]
	v_pk_fma_f32 v[24:25], v[142:143], v[124:125], v[24:25]
	v_lshlrev_b32_e32 v122, 16, v88
	v_and_b32_e32 v123, 0xffff0000, v88
	v_lshlrev_b32_e32 v124, 16, v89
	v_and_b32_e32 v125, 0xffff0000, v89
	v_pk_mul_f32 v[122:123], v[116:117], v[122:123] op_sel_hi:[0,1]
	v_pk_mul_f32 v[124:125], v[116:117], v[124:125] op_sel_hi:[0,1]
	v_pk_mul_f32 v[122:123], v[144:145], v[122:123]
	v_pk_mul_f32 v[124:125], v[146:147], v[124:125]
	v_pk_fma_f32 v[38:39], v[140:141], v[122:123], v[38:39]
	v_pk_fma_f32 v[40:41], v[142:143], v[124:125], v[40:41]
	v_lshlrev_b32_e32 v122, 16, v96
	v_and_b32_e32 v123, 0xffff0000, v96
	v_lshlrev_b32_e32 v124, 16, v97
	v_and_b32_e32 v125, 0xffff0000, v97
	v_pk_mul_f32 v[122:123], v[118:119], v[122:123] op_sel_hi:[0,1]
	v_pk_mul_f32 v[124:125], v[118:119], v[124:125] op_sel_hi:[0,1]
	v_pk_mul_f32 v[122:123], v[144:145], v[122:123]
	v_pk_mul_f32 v[124:125], v[146:147], v[124:125]
	v_pk_fma_f32 v[54:55], v[140:141], v[122:123], v[54:55]
	v_pk_fma_f32 v[56:57], v[142:143], v[124:125], v[56:57]
	v_lshlrev_b32_e32 v122, 16, v104
	v_and_b32_e32 v123, 0xffff0000, v104
	v_lshlrev_b32_e32 v124, 16, v105
	v_and_b32_e32 v125, 0xffff0000, v105
	v_pk_mul_f32 v[122:123], v[120:121], v[122:123] op_sel_hi:[0,1]
	v_pk_mul_f32 v[124:125], v[120:121], v[124:125] op_sel_hi:[0,1]
	v_pk_mul_f32 v[122:123], v[144:145], v[122:123]
	v_pk_mul_f32 v[124:125], v[146:147], v[124:125]
	v_pk_fma_f32 v[70:71], v[140:141], v[122:123], v[70:71]
	v_pk_fma_f32 v[72:73], v[142:143], v[124:125], v[72:73]
	global_store_dwordx4 v3, v[10:13], s[26:27]
	global_store_dwordx4 v3, v[14:17], s[26:27] offset:1024
	global_store_dwordx4 v3, v[18:21], s[26:27] offset:2048
	global_store_dwordx4 v3, v[22:25], s[26:27] offset:3072
	s_add_u32 s26, s26, 0x1000
	s_addc_u32 s27, s27, 0
	global_store_dwordx4 v3, v[26:29], s[26:27]
	global_store_dwordx4 v3, v[30:33], s[26:27] offset:1024
	global_store_dwordx4 v3, v[34:37], s[26:27] offset:2048
	global_store_dwordx4 v3, v[38:41], s[26:27] offset:3072
	s_add_u32 s26, s26, 0x1000
	s_addc_u32 s27, s27, 0
	global_store_dwordx4 v3, v[42:45], s[26:27]
	global_store_dwordx4 v3, v[46:49], s[26:27] offset:1024
	global_store_dwordx4 v3, v[50:53], s[26:27] offset:2048
	global_store_dwordx4 v3, v[54:57], s[26:27] offset:3072
	s_add_u32 s26, s26, 0x1000
	s_addc_u32 s27, s27, 0
	global_store_dwordx4 v3, v[58:61], s[26:27]
	global_store_dwordx4 v3, v[62:65], s[26:27] offset:1024
	global_store_dwordx4 v3, v[66:69], s[26:27] offset:2048
	global_store_dwordx4 v3, v[70:73], s[26:27] offset:3072
	s_bitcmp1_b32 s43, 0
	s_cbranch_scc0 .Lrows_next
	v_mul_f32_e32 v122, v11, v11
	v_mul_f32_e32 v126, v27, v27
	v_mul_f32_e32 v132, v43, v43
	v_mul_f32_e32 v136, v59, v59
	v_fma_f32 v122, v10, v10, v122
	v_fma_f32 v126, v26, v26, v126
	v_fma_f32 v132, v42, v42, v132
	v_fma_f32 v136, v58, v58, v136
	v_fma_f32 v122, v12, v12, v122
	v_fma_f32 v126, v28, v28, v126
	v_fma_f32 v132, v44, v44, v132
	v_fma_f32 v136, v60, v60, v136
	v_fma_f32 v122, v13, v13, v122
	v_fma_f32 v126, v29, v29, v126
	v_fma_f32 v132, v45, v45, v132
	v_fma_f32 v136, v61, v61, v136
	v_mul_f32_e32 v123, v15, v15
	v_mul_f32_e32 v127, v31, v31
	v_mul_f32_e32 v133, v47, v47
	v_mul_f32_e32 v137, v63, v63
	v_fma_f32 v123, v14, v14, v123
	v_fma_f32 v127, v30, v30, v127
	v_fma_f32 v133, v46, v46, v133
	v_fma_f32 v137, v62, v62, v137
	v_fma_f32 v123, v16, v16, v123
	v_fma_f32 v127, v32, v32, v127
	v_fma_f32 v133, v48, v48, v133
	v_fma_f32 v137, v64, v64, v137
	v_fma_f32 v123, v17, v17, v123
	v_fma_f32 v127, v33, v33, v127
	v_fma_f32 v133, v49, v49, v133
	v_fma_f32 v137, v65, v65, v137
	v_mul_f32_e32 v124, v19, v19
	v_mul_f32_e32 v128, v35, v35
	v_mul_f32_e32 v134, v51, v51
	v_mul_f32_e32 v138, v67, v67
	v_fma_f32 v124, v18, v18, v124
	v_fma_f32 v128, v34, v34, v128
	v_fma_f32 v134, v50, v50, v134
	v_fma_f32 v138, v66, v66, v138
	v_fma_f32 v124, v20, v20, v124
	v_fma_f32 v128, v36, v36, v128
	v_fma_f32 v134, v52, v52, v134
	v_fma_f32 v138, v68, v68, v138
	v_fma_f32 v124, v21, v21, v124
	v_fma_f32 v128, v37, v37, v128
	v_fma_f32 v134, v53, v53, v134
	v_fma_f32 v138, v69, v69, v138
	v_mul_f32_e32 v125, v23, v23
	v_mul_f32_e32 v129, v39, v39
	v_mul_f32_e32 v135, v55, v55
	v_mul_f32_e32 v139, v71, v71
	v_fma_f32 v125, v22, v22, v125
	v_fma_f32 v129, v38, v38, v129
	v_fma_f32 v135, v54, v54, v135
	v_fma_f32 v139, v70, v70, v139
	v_fma_f32 v125, v24, v24, v125
	v_fma_f32 v129, v40, v40, v129
	v_fma_f32 v135, v56, v56, v135
	v_fma_f32 v139, v72, v72, v139
	v_fma_f32 v125, v25, v25, v125
	v_fma_f32 v129, v41, v41, v129
	v_fma_f32 v135, v57, v57, v135
	v_fma_f32 v139, v73, v73, v139
	v_add_f32_e32 v106, v122, v123
	v_add_f32_e32 v107, v126, v127
	v_add_f32_e32 v108, v132, v133
	v_add_f32_e32 v109, v136, v137
	v_add_f32_e32 v106, v106, v124
	v_add_f32_e32 v107, v107, v128
	v_add_f32_e32 v108, v108, v134
	v_add_f32_e32 v109, v109, v138
	v_add_f32_e32 v106, v106, v125
	v_add_f32_e32 v107, v107, v129
	v_add_f32_e32 v108, v108, v135
	v_add_f32_e32 v109, v109, v139
	v_mov_b32_e32 v110, v106
	v_mov_b32_e32 v111, v107
	v_mov_b32_e32 v112, v108
	v_mov_b32_e32 v113, v109
	v_permlane32_swap_b32_e32 v106, v110
	v_permlane32_swap_b32_e32 v107, v111
	v_permlane32_swap_b32_e32 v108, v112
	v_permlane32_swap_b32_e32 v109, v113
	v_add_f32_e32 v106, v106, v110
	v_add_f32_e32 v107, v107, v111
	v_add_f32_e32 v108, v108, v112
	v_add_f32_e32 v109, v109, v113
	v_mov_b32_e32 v110, v106
	v_mov_b32_e32 v111, v107
	v_mov_b32_e32 v112, v108
	v_mov_b32_e32 v113, v109
	v_permlane16_swap_b32_e32 v106, v110
	v_permlane16_swap_b32_e32 v107, v111
	v_permlane16_swap_b32_e32 v108, v112
	v_permlane16_swap_b32_e32 v109, v113
	v_add_f32_e32 v106, v106, v110
	v_add_f32_e32 v107, v107, v111
	v_add_f32_e32 v108, v108, v112
	v_add_f32_e32 v109, v109, v113
	v_add_f32_dpp v106, v106, v106 row_ror:8 row_mask:0xf bank_mask:0xf
	v_add_f32_dpp v107, v107, v107 row_ror:8 row_mask:0xf bank_mask:0xf
	v_add_f32_dpp v108, v108, v108 row_ror:8 row_mask:0xf bank_mask:0xf
	v_add_f32_dpp v109, v109, v109 row_ror:8 row_mask:0xf bank_mask:0xf
	v_add_f32_dpp v110, v106, v106 row_shl:4 row_mask:0xf bank_mask:0x5
	v_add_f32_dpp v111, v107, v107 row_shl:4 row_mask:0xf bank_mask:0x5
	v_add_f32_dpp v112, v108, v108 row_shl:4 row_mask:0xf bank_mask:0x5
	v_add_f32_dpp v113, v109, v109 row_shl:4 row_mask:0xf bank_mask:0x5
	v_add_f32_dpp v110, v106, v106 row_shr:4 row_mask:0xf bank_mask:0xa
	v_add_f32_dpp v111, v107, v107 row_shr:4 row_mask:0xf bank_mask:0xa
	v_add_f32_dpp v112, v108, v108 row_shr:4 row_mask:0xf bank_mask:0xa
	v_add_f32_dpp v113, v109, v109 row_shr:4 row_mask:0xf bank_mask:0xa
	v_add_f32_dpp v106, v110, v110 quad_perm:[2,3,0,1] row_mask:0xf bank_mask:0xf
	v_add_f32_dpp v107, v111, v111 quad_perm:[2,3,0,1] row_mask:0xf bank_mask:0xf
	v_add_f32_dpp v108, v112, v112 quad_perm:[2,3,0,1] row_mask:0xf bank_mask:0xf
	v_add_f32_dpp v109, v113, v113 quad_perm:[2,3,0,1] row_mask:0xf bank_mask:0xf
	v_add_f32_dpp v110, v106, v106 quad_perm:[1,0,3,2] row_mask:0xf bank_mask:0xf
	v_add_f32_dpp v111, v107, v107 quad_perm:[1,0,3,2] row_mask:0xf bank_mask:0xf
	v_add_f32_dpp v112, v108, v108 quad_perm:[1,0,3,2] row_mask:0xf bank_mask:0xf
	v_add_f32_dpp v113, v109, v109 quad_perm:[1,0,3,2] row_mask:0xf bank_mask:0xf
	v_fmamk_f32 v110, v110, 0x3a800000, v198
	v_fmamk_f32 v111, v111, 0x3a800000, v198
	v_fmamk_f32 v112, v112, 0x3a800000, v198
	v_fmamk_f32 v113, v113, 0x3a800000, v198
	v_rsq_f32_e32 v114, v110
	v_rsq_f32_e32 v116, v111
	v_rsq_f32_e32 v118, v112
	v_rsq_f32_e32 v120, v113
	ds_read_b128 v[140:143], v6 offset:4096
	ds_read_b128 v[144:147], v5 offset:20480
	ds_read_b128 v[122:125], v5 offset:40960
	s_waitcnt lgkmcnt(0)
	v_pk_add_f32 v[122:123], v[122:123], 1.0 op_sel_hi:[1,0]
	v_pk_add_f32 v[124:125], v[124:125], 1.0 op_sel_hi:[1,0]
	v_pk_mul_f32 v[10:11], v[10:11], v[114:115] op_sel_hi:[1,0]
	v_pk_mul_f32 v[12:13], v[12:13], v[114:115] op_sel_hi:[1,0]
	v_pk_mul_f32 v[10:11], v[140:141], v[10:11]
	v_pk_mul_f32 v[12:13], v[142:143], v[12:13]
	v_pk_fma_f32 v[10:11], v[122:123], v[10:11], v[144:145]
	v_pk_fma_f32 v[12:13], v[124:125], v[12:13], v[146:147]
	v_cvt_pk_bf16_f32 v10, v10, v11
	v_cvt_pk_bf16_f32 v11, v12, v13
	v_pk_mul_f32 v[26:27], v[26:27], v[116:117] op_sel_hi:[1,0]
	v_pk_mul_f32 v[28:29], v[28:29], v[116:117] op_sel_hi:[1,0]
	v_pk_mul_f32 v[26:27], v[140:141], v[26:27]
	v_pk_mul_f32 v[28:29], v[142:143], v[28:29]
	v_pk_fma_f32 v[26:27], v[122:123], v[26:27], v[144:145]
	v_pk_fma_f32 v[28:29], v[124:125], v[28:29], v[146:147]
	v_cvt_pk_bf16_f32 v26, v26, v27
	v_cvt_pk_bf16_f32 v27, v28, v29
	v_pk_mul_f32 v[42:43], v[42:43], v[118:119] op_sel_hi:[1,0]
	v_pk_mul_f32 v[44:45], v[44:45], v[118:119] op_sel_hi:[1,0]
	v_pk_mul_f32 v[42:43], v[140:141], v[42:43]
	v_pk_mul_f32 v[44:45], v[142:143], v[44:45]
	v_pk_fma_f32 v[42:43], v[122:123], v[42:43], v[144:145]
	v_pk_fma_f32 v[44:45], v[124:125], v[44:45], v[146:147]
	v_cvt_pk_bf16_f32 v42, v42, v43
	v_cvt_pk_bf16_f32 v43, v44, v45
	v_pk_mul_f32 v[58:59], v[58:59], v[120:121] op_sel_hi:[1,0]
	v_pk_mul_f32 v[60:61], v[60:61], v[120:121] op_sel_hi:[1,0]
	v_pk_mul_f32 v[58:59], v[140:141], v[58:59]
	v_pk_mul_f32 v[60:61], v[142:143], v[60:61]
	v_pk_fma_f32 v[58:59], v[122:123], v[58:59], v[144:145]
	v_pk_fma_f32 v[60:61], v[124:125], v[60:61], v[146:147]
	v_cvt_pk_bf16_f32 v58, v58, v59
	v_cvt_pk_bf16_f32 v59, v60, v61
	ds_read_b128 v[140:143], v6 offset:5120
	ds_read_b128 v[144:147], v5 offset:21504
	ds_read_b128 v[122:125], v5 offset:41984
	s_waitcnt lgkmcnt(0)
	v_pk_add_f32 v[122:123], v[122:123], 1.0 op_sel_hi:[1,0]
	v_pk_add_f32 v[124:125], v[124:125], 1.0 op_sel_hi:[1,0]
	v_pk_mul_f32 v[14:15], v[14:15], v[114:115] op_sel_hi:[1,0]
	v_pk_mul_f32 v[16:17], v[16:17], v[114:115] op_sel_hi:[1,0]
	v_pk_mul_f32 v[14:15], v[140:141], v[14:15]
	v_pk_mul_f32 v[16:17], v[142:143], v[16:17]
	v_pk_fma_f32 v[14:15], v[122:123], v[14:15], v[144:145]
	v_pk_fma_f32 v[16:17], v[124:125], v[16:17], v[146:147]
	v_cvt_pk_bf16_f32 v14, v14, v15
	v_cvt_pk_bf16_f32 v15, v16, v17
	v_pk_mul_f32 v[30:31], v[30:31], v[116:117] op_sel_hi:[1,0]
	v_pk_mul_f32 v[32:33], v[32:33], v[116:117] op_sel_hi:[1,0]
	v_pk_mul_f32 v[30:31], v[140:141], v[30:31]
	v_pk_mul_f32 v[32:33], v[142:143], v[32:33]
	v_pk_fma_f32 v[30:31], v[122:123], v[30:31], v[144:145]
	v_pk_fma_f32 v[32:33], v[124:125], v[32:33], v[146:147]
	v_cvt_pk_bf16_f32 v30, v30, v31
	v_cvt_pk_bf16_f32 v31, v32, v33
	v_pk_mul_f32 v[46:47], v[46:47], v[118:119] op_sel_hi:[1,0]
	v_pk_mul_f32 v[48:49], v[48:49], v[118:119] op_sel_hi:[1,0]
	v_pk_mul_f32 v[46:47], v[140:141], v[46:47]
	v_pk_mul_f32 v[48:49], v[142:143], v[48:49]
	v_pk_fma_f32 v[46:47], v[122:123], v[46:47], v[144:145]
	v_pk_fma_f32 v[48:49], v[124:125], v[48:49], v[146:147]
	v_cvt_pk_bf16_f32 v46, v46, v47
	v_cvt_pk_bf16_f32 v47, v48, v49
	v_pk_mul_f32 v[62:63], v[62:63], v[120:121] op_sel_hi:[1,0]
	v_pk_mul_f32 v[64:65], v[64:65], v[120:121] op_sel_hi:[1,0]
	v_pk_mul_f32 v[62:63], v[140:141], v[62:63]
	v_pk_mul_f32 v[64:65], v[142:143], v[64:65]
	v_pk_fma_f32 v[62:63], v[122:123], v[62:63], v[144:145]
	v_pk_fma_f32 v[64:65], v[124:125], v[64:65], v[146:147]
	v_cvt_pk_bf16_f32 v62, v62, v63
	v_cvt_pk_bf16_f32 v63, v64, v65
	ds_read_b128 v[140:143], v6 offset:6144
	ds_read_b128 v[144:147], v5 offset:22528
	ds_read_b128 v[122:125], v5 offset:43008
	s_waitcnt lgkmcnt(0)
	v_pk_add_f32 v[122:123], v[122:123], 1.0 op_sel_hi:[1,0]
	v_pk_add_f32 v[124:125], v[124:125], 1.0 op_sel_hi:[1,0]
	v_pk_mul_f32 v[18:19], v[18:19], v[114:115] op_sel_hi:[1,0]
	v_pk_mul_f32 v[20:21], v[20:21], v[114:115] op_sel_hi:[1,0]
	v_pk_mul_f32 v[18:19], v[140:141], v[18:19]
	v_pk_mul_f32 v[20:21], v[142:143], v[20:21]
	v_pk_fma_f32 v[18:19], v[122:123], v[18:19], v[144:145]
	v_pk_fma_f32 v[20:21], v[124:125], v[20:21], v[146:147]
	v_cvt_pk_bf16_f32 v18, v18, v19
	v_cvt_pk_bf16_f32 v19, v20, v21
	v_pk_mul_f32 v[34:35], v[34:35], v[116:117] op_sel_hi:[1,0]
	v_pk_mul_f32 v[36:37], v[36:37], v[116:117] op_sel_hi:[1,0]
	v_pk_mul_f32 v[34:35], v[140:141], v[34:35]
	v_pk_mul_f32 v[36:37], v[142:143], v[36:37]
	v_pk_fma_f32 v[34:35], v[122:123], v[34:35], v[144:145]
	v_pk_fma_f32 v[36:37], v[124:125], v[36:37], v[146:147]
	v_cvt_pk_bf16_f32 v34, v34, v35
	v_cvt_pk_bf16_f32 v35, v36, v37
	v_pk_mul_f32 v[50:51], v[50:51], v[118:119] op_sel_hi:[1,0]
	v_pk_mul_f32 v[52:53], v[52:53], v[118:119] op_sel_hi:[1,0]
	v_pk_mul_f32 v[50:51], v[140:141], v[50:51]
	v_pk_mul_f32 v[52:53], v[142:143], v[52:53]
	v_pk_fma_f32 v[50:51], v[122:123], v[50:51], v[144:145]
	v_pk_fma_f32 v[52:53], v[124:125], v[52:53], v[146:147]
	v_cvt_pk_bf16_f32 v50, v50, v51
	v_cvt_pk_bf16_f32 v51, v52, v53
	v_pk_mul_f32 v[66:67], v[66:67], v[120:121] op_sel_hi:[1,0]
	v_pk_mul_f32 v[68:69], v[68:69], v[120:121] op_sel_hi:[1,0]
	v_pk_mul_f32 v[66:67], v[140:141], v[66:67]
	v_pk_mul_f32 v[68:69], v[142:143], v[68:69]
	v_pk_fma_f32 v[66:67], v[122:123], v[66:67], v[144:145]
	v_pk_fma_f32 v[68:69], v[124:125], v[68:69], v[146:147]
	v_cvt_pk_bf16_f32 v66, v66, v67
	v_cvt_pk_bf16_f32 v67, v68, v69
	ds_read_b128 v[140:143], v6 offset:7168
	ds_read_b128 v[144:147], v5 offset:23552
	ds_read_b128 v[122:125], v5 offset:44032
	s_waitcnt lgkmcnt(0)
	v_pk_add_f32 v[122:123], v[122:123], 1.0 op_sel_hi:[1,0]
	v_pk_add_f32 v[124:125], v[124:125], 1.0 op_sel_hi:[1,0]
	v_pk_mul_f32 v[22:23], v[22:23], v[114:115] op_sel_hi:[1,0]
	v_pk_mul_f32 v[24:25], v[24:25], v[114:115] op_sel_hi:[1,0]
	v_pk_mul_f32 v[22:23], v[140:141], v[22:23]
	v_pk_mul_f32 v[24:25], v[142:143], v[24:25]
	v_pk_fma_f32 v[22:23], v[122:123], v[22:23], v[144:145]
	v_pk_fma_f32 v[24:25], v[124:125], v[24:25], v[146:147]
	v_cvt_pk_bf16_f32 v22, v22, v23
	v_cvt_pk_bf16_f32 v23, v24, v25
	v_pk_mul_f32 v[38:39], v[38:39], v[116:117] op_sel_hi:[1,0]
	v_pk_mul_f32 v[40:41], v[40:41], v[116:117] op_sel_hi:[1,0]
	v_pk_mul_f32 v[38:39], v[140:141], v[38:39]
	v_pk_mul_f32 v[40:41], v[142:143], v[40:41]
	v_pk_fma_f32 v[38:39], v[122:123], v[38:39], v[144:145]
	v_pk_fma_f32 v[40:41], v[124:125], v[40:41], v[146:147]
	v_cvt_pk_bf16_f32 v38, v38, v39
	v_cvt_pk_bf16_f32 v39, v40, v41
	v_pk_mul_f32 v[54:55], v[54:55], v[118:119] op_sel_hi:[1,0]
	v_pk_mul_f32 v[56:57], v[56:57], v[118:119] op_sel_hi:[1,0]
	v_pk_mul_f32 v[54:55], v[140:141], v[54:55]
	v_pk_mul_f32 v[56:57], v[142:143], v[56:57]
	v_pk_fma_f32 v[54:55], v[122:123], v[54:55], v[144:145]
	v_pk_fma_f32 v[56:57], v[124:125], v[56:57], v[146:147]
	v_cvt_pk_bf16_f32 v54, v54, v55
	v_cvt_pk_bf16_f32 v55, v56, v57
	v_pk_mul_f32 v[70:71], v[70:71], v[120:121] op_sel_hi:[1,0]
	v_pk_mul_f32 v[72:73], v[72:73], v[120:121] op_sel_hi:[1,0]
	v_pk_mul_f32 v[70:71], v[140:141], v[70:71]
	v_pk_mul_f32 v[72:73], v[142:143], v[72:73]
	v_pk_fma_f32 v[70:71], v[122:123], v[70:71], v[144:145]
	v_pk_fma_f32 v[72:73], v[124:125], v[72:73], v[146:147]
	v_cvt_pk_bf16_f32 v70, v70, v71
	v_cvt_pk_bf16_f32 v71, v72, v73
	global_store_dwordx2 v4, v[10:11], s[40:41]
	global_store_dwordx2 v4, v[14:15], s[40:41] offset:512
	global_store_dwordx2 v4, v[18:19], s[40:41] offset:1024
	global_store_dwordx2 v4, v[22:23], s[40:41] offset:1536
	s_add_u32 s40, s40, 0x800
	s_addc_u32 s41, s41, 0
	global_store_dwordx2 v4, v[26:27], s[40:41]
	global_store_dwordx2 v4, v[30:31], s[40:41] offset:512
	global_store_dwordx2 v4, v[34:35], s[40:41] offset:1024
	global_store_dwordx2 v4, v[38:39], s[40:41] offset:1536
	s_add_u32 s40, s40, 0x800
	s_addc_u32 s41, s41, 0
	global_store_dwordx2 v4, v[42:43], s[40:41]
	global_store_dwordx2 v4, v[46:47], s[40:41] offset:512
	global_store_dwordx2 v4, v[50:51], s[40:41] offset:1024
	global_store_dwordx2 v4, v[54:55], s[40:41] offset:1536
	s_add_u32 s40, s40, 0x800
	s_addc_u32 s41, s41, 0
	global_store_dwordx2 v4, v[58:59], s[40:41]
	global_store_dwordx2 v4, v[62:63], s[40:41] offset:512
	global_store_dwordx2 v4, v[66:67], s[40:41] offset:1024
	global_store_dwordx2 v4, v[70:71], s[40:41] offset:1536
.Lrows_next:
	s_add_i32 s20, s20, s21
	s_cmp_ge_i32 s20, s2
	s_cbranch_scc0 .Lrows_item
	s_cmp_eq_u32 s44, 0
	s_cbranch_scc1 .LBB0_168
	s_branch .LBB0_113

.LBB0_293:
	s_andn2_b64 vcc, exec, s[94:95]
	s_mov_b64 s[94:95], s[8:9]
	s_cbranch_vccnz .LBB0_208
	v_mov_b32_e32 v100, v196
	s_movk_i32 s13, 0xffe0
	v_and_b32_e32 v6, 15, v100
	v_bfe_u32 v8, v100, 4, 2
	v_ashrrev_i32_e32 v0, 1, v100
	v_and_or_b32 v132, v0, s13, v6
	v_lshlrev_b32_e32 v0, 4, v8
	v_lshl_add_u64 v[2:3], s[90:91], 0, v[0:1]
	s_movk_i32 s12, 0x600
	v_mad_i64_i32 v[4:5], s[10:11], v132, s12, v[2:3]
	global_load_dwordx4 v[46:49], v[4:5], off
	global_load_dwordx4 v[42:45], v[4:5], off offset:64
	v_or_b32_e32 v130, 16, v132
	v_mad_i64_i32 v[2:3], s[10:11], v130, s12, v[2:3]
	global_load_dwordx4 v[50:53], v[4:5], off offset:128
	global_load_dwordx4 v[62:65], v[2:3], off
	global_load_dwordx4 v[58:61], v[2:3], off offset:64
	global_load_dwordx4 v[54:57], v[2:3], off offset:128
	v_lshrrev_b32_e32 v2, 1, v100
	v_lshrrev_b32_e32 v7, 4, v100
	v_ashrrev_i32_e32 v101, 2, v100
	v_and_b32_e32 v2, 24, v2
	v_lshlrev_b32_e32 v140, 2, v8
	v_and_or_b32 v2, v101, s13, v2
	v_and_b32_e32 v3, 4, v7
	v_and_b32_e32 v5, 3, v101
	v_lshrrev_b32_e64 v0, v140, s57
	v_or3_b32 v102, v2, v3, v5
	s_movk_i32 s10, 0x60
	v_xor_b32_e32 v4, v0, v100
	v_mad_i64_i32 v[2:3], s[10:11], v102, s10, 0
	s_mul_i32 s0, s93, 0x18c000
	s_mul_hi_u32 s4, s92, 0x18c000
	v_lshlrev_b32_e32 v4, 3, v4
	s_movk_i32 s10, 0x2100
	s_add_i32 s4, s4, s0
	s_mul_i32 s5, s92, 0x18c000
	v_readlane_b32 s0, v224, 7
	v_and_b32_e32 v8, 24, v4
	v_mad_i64_i32 v[4:5], s[10:11], v101, s10, 0
	s_add_u32 s0, s0, s5
	v_readlane_b32 s1, v224, 8
	v_or_b32_e32 v2, v2, v8
	v_or_b32_e32 v4, v4, v8
	v_and_b32_e32 v8, 12, v100
	s_addc_u32 s1, s1, s4
	v_lshl_add_u32 v142, v100, 4, 0
	v_lshrrev_b32_e64 v8, v8, s57
	v_xor_b32_e32 v7, v8, v7
	v_lshl_add_u64 v[2:3], v[2:3], 1, s[0:1]
	v_readfirstlane_b32 s0, v142
	v_add_u32_e32 v8, 0x1000, v142
	v_lshlrev_b32_e32 v6, 6, v6
	v_lshlrev_b32_e32 v7, 4, v7
	s_waitcnt vmcnt(0)
	s_mov_b32 m0, s0
	v_readfirstlane_b32 s0, v8
	v_add_u32_e32 v8, 0x2000, v142
	s_mul_i32 s6, s93, 0x108000
	s_mul_hi_u32 s7, s92, 0x108000
	v_and_or_b32 v141, v7, 48, v6
	global_load_lds_dwordx4 v[2:3], off
	v_lshl_add_u64 v[6:7], v[2:3], 0, 64
	s_mov_b32 m0, s0
	v_readfirstlane_b32 s0, v8
	s_add_i32 s6, s7, s6
	s_mul_i32 s7, s92, 0x108000
	v_readlane_b32 s8, v224, 9
	global_load_lds_dwordx4 v[6:7], off
	v_lshl_add_u64 v[6:7], v[2:3], 0, s[78:79]
	s_mov_b32 m0, s0
	s_add_u32 s8, s8, s7
	v_readlane_b32 s9, v224, 10
	global_load_lds_dwordx4 v[6:7], off
	v_add_u32_e32 v6, 0x3000, v142
	s_addc_u32 s9, s9, s6
	v_readfirstlane_b32 s0, v6
	v_add_u32_e32 v8, 0x4000, v142
	v_lshl_add_u64 v[4:5], v[4:5], 1, s[8:9]
	s_mov_b32 m0, s0
	v_readfirstlane_b32 s0, v8
	v_add_u32_e32 v8, 0x5000, v142
	global_load_lds_dwordx4 v[4:5], off
	v_lshl_add_u64 v[6:7], v[4:5], 0, 64
	s_mov_b32 m0, s0
	v_readfirstlane_b32 s0, v8
	global_load_lds_dwordx4 v[6:7], off
	v_lshl_add_u64 v[6:7], v[2:3], 0, s[24:25]
	s_mov_b32 m0, s0
	s_mov_b64 s[0:1], 0x3040
	v_add_u32_e32 v8, 0x6000, v142
	global_load_lds_dwordx4 v[6:7], off
	v_lshl_add_u64 v[6:7], v[2:3], 0, s[0:1]
	v_readfirstlane_b32 s0, v8
	s_mov_b32 m0, s0
	s_mov_b64 s[0:1], 0x3080
	v_add_u32_e32 v8, 0x7000, v142
	global_load_lds_dwordx4 v[6:7], off
	v_lshl_add_u64 v[6:7], v[2:3], 0, s[0:1]
	v_readfirstlane_b32 s0, v8
	v_add_u32_e32 v8, 0x8000, v142
	s_mov_b32 m0, s0
	v_readfirstlane_b32 s0, v8
	v_add_u32_e32 v8, 0x9000, v142
	global_load_lds_dwordx4 v[6:7], off
	v_lshl_add_u64 v[6:7], v[4:5], 0, s[78:79]
	s_mov_b32 m0, s0
	v_readfirstlane_b32 s0, v8
	global_load_lds_dwordx4 v[6:7], off
	v_lshl_add_u64 v[6:7], v[4:5], 0, s[84:85]
	s_mov_b32 m0, s0
	v_add_u32_e32 v8, 0xa000, v142
	s_mov_b64 s[0:1], 0x6000
	global_load_lds_dwordx4 v[6:7], off
	v_lshl_add_u64 v[6:7], v[2:3], 0, s[0:1]
	v_readfirstlane_b32 s0, v8
	s_waitcnt vmcnt(5) lgkmcnt(0)
	s_barrier
	s_mov_b32 m0, s0
	s_mov_b64 s[0:1], 0x6040
	v_add_u32_e32 v8, 0xb000, v142
	global_load_lds_dwordx4 v[6:7], off
	v_lshl_add_u64 v[6:7], v[2:3], 0, s[0:1]
	v_readfirstlane_b32 s0, v8
	s_mov_b32 m0, s0
	s_mov_b64 s[0:1], 0x6080
	global_load_lds_dwordx4 v[6:7], off
	v_add_u32_e32 v6, 0xc000, v142
	v_lshl_add_u64 v[2:3], v[2:3], 0, s[0:1]
	v_readfirstlane_b32 s0, v6
	s_mov_b32 m0, s0
	s_mov_b64 s[0:1], 0x100
	v_add_u32_e32 v6, 0xd000, v142
	global_load_lds_dwordx4 v[2:3], off
	v_lshl_add_u64 v[2:3], v[4:5], 0, s[0:1]
	v_readfirstlane_b32 s0, v6
	s_mov_b32 m0, s0
	s_mov_b64 s[0:1], 0x140
	global_load_lds_dwordx4 v[2:3], off
	v_lshl_add_u64 v[2:3], v[4:5], 0, s[0:1]
	v_add_u32_e32 v4, 0xe000, v142
	v_add_u32_e32 v143, 0, v141
	v_readfirstlane_b32 s0, v4
	s_mov_b32 m0, s0
	s_mov_b32 s81, s80
	global_load_lds_dwordx4 v[2:3], off
	ds_read_b128 v[2:5], v143
	ds_read_b128 v[6:9], v143 offset:1024
	s_waitcnt vmcnt(0) lgkmcnt(0)
	v_mfma_f32_16x16x32_bf16 v[10:13], v[2:5], v[46:49], 0
	ds_read_b128 v[14:17], v143 offset:4096
	ds_read_b128 v[18:21], v143 offset:5120
	s_mov_b32 s82, s80
	s_mov_b32 s83, s80
	v_mfma_f32_16x16x32_bf16 v[2:5], v[2:5], v[62:65], 0
	s_add_u32 s8, s22, s5
	s_addc_u32 s9, s23, s4
	v_bitop3_b32 v0, v0, 3, v100 bitop3:0x48
	s_waitcnt lgkmcnt(1)
	v_mfma_f32_16x16x32_bf16 v[10:13], v[14:17], v[42:45], v[10:13]
	s_mov_b32 s0, 1
	v_ashrrev_i32_e32 v133, 31, v132
	v_ashrrev_i32_e32 v131, 31, v130
	v_mfma_f32_16x16x32_bf16 v[2:5], v[14:17], v[58:61], v[2:5]
	ds_read_b128 v[14:17], v143 offset:8192
	ds_read_b128 v[22:25], v143 offset:9216
	s_mov_b32 s1, 2
	v_lshlrev_b32_e32 v0, 4, v0
	s_waitcnt lgkmcnt(1)
	v_mfma_f32_16x16x32_bf16 v[10:13], v[14:17], v[50:53], v[10:13]
	v_mfma_f32_16x16x32_bf16 v[2:5], v[14:17], v[54:57], v[2:5]
	v_mfma_f32_16x16x32_bf16 v[14:17], v[6:9], v[46:49], 0
	v_mfma_f32_16x16x32_bf16 v[6:9], v[6:9], v[62:65], 0
	v_mfma_f32_16x16x32_bf16 v[14:17], v[18:21], v[42:45], v[14:17]
	v_mfma_f32_16x16x32_bf16 v[6:9], v[18:21], v[58:61], v[6:9]
	s_waitcnt lgkmcnt(0)
	v_mfma_f32_16x16x32_bf16 v[14:17], v[22:25], v[50:53], v[14:17]
	v_mfma_f32_16x16x32_bf16 v[6:9], v[22:25], v[54:57], v[6:9]
	ds_read_b128 v[18:21], v143 offset:2048
	ds_read_b128 v[22:25], v143 offset:3072
	ds_read_b128 v[30:33], v143 offset:6144
	ds_read_b128 v[34:37], v143 offset:7168
	s_waitcnt lgkmcnt(3)
	v_mfma_f32_16x16x32_bf16 v[26:29], v[18:21], v[46:49], 0
	v_mfma_f32_16x16x32_bf16 v[18:21], v[18:21], v[62:65], 0
	s_waitcnt lgkmcnt(1)
	v_mfma_f32_16x16x32_bf16 v[26:29], v[30:33], v[42:45], v[26:29]
	v_mfma_f32_16x16x32_bf16 v[18:21], v[30:33], v[58:61], v[18:21]
	ds_read_b128 v[30:33], v143 offset:10240
	ds_read_b128 v[38:41], v143 offset:11264
	s_waitcnt lgkmcnt(1)
	v_mfma_f32_16x16x32_bf16 v[26:29], v[30:33], v[50:53], v[26:29]
	v_mfma_f32_16x16x32_bf16 v[18:21], v[30:33], v[54:57], v[18:21]
	v_mfma_f32_16x16x32_bf16 v[30:33], v[22:25], v[46:49], 0
	v_mfma_f32_16x16x32_bf16 v[22:25], v[22:25], v[62:65], 0
	v_mfma_f32_16x16x32_bf16 v[30:33], v[34:37], v[42:45], v[30:33]
	v_mfma_f32_16x16x32_bf16 v[22:25], v[34:37], v[58:61], v[22:25]
	v_max_f32_e32 v34, v11, v11
	v_max_f32_e32 v35, v10, v10
	v_max_f32_e32 v34, v35, v34
	v_max3_f32 v34, v34, v12, v13
	s_waitcnt lgkmcnt(0)
	v_mfma_f32_16x16x32_bf16 v[30:33], v[38:41], v[50:53], v[30:33]
	v_max3_f32 v34, v34, v14, v15
	v_max3_f32 v34, v34, v16, v17
	v_max3_f32 v34, v34, v26, v27
	v_max3_f32 v34, v34, v28, v29
	v_mfma_f32_16x16x32_bf16 v[22:25], v[38:41], v[54:57], v[22:25]
	s_nop 2
	v_max3_f32 v34, v34, v30, v31
	v_max3_f32 v34, v34, v32, v33
	v_mov_b32_e32 v35, v34
	s_nop 1
	v_permlane32_swap_b32_e32 v34, v35
	v_max_f32_e32 v35, v35, v35
	v_max_f32_e32 v34, v34, v34
	v_max_f32_e32 v34, v34, v35
	v_mov_b32_e32 v35, v34
	s_nop 1
	v_permlane16_swap_b32_e32 v34, v35
	v_max_f32_e32 v35, v35, v35
	v_max_f32_e32 v34, v34, v34
	v_max_f32_e32 v98, v34, v35
	v_sub_f32_e32 v11, v11, v98
	v_sub_f32_e32 v10, v10, v98
	v_exp_f32_e32 v10, v10
	v_exp_f32_e32 v11, v11
	v_sub_f32_e32 v27, v27, v98
	v_sub_f32_e32 v26, v26, v98
	v_sub_f32_e32 v17, v17, v98
	v_cvt_pk_bf16_f32 v78, v10, v11
	v_exp_f32_e32 v10, v26
	v_exp_f32_e32 v11, v27
	v_sub_f32_e32 v16, v16, v98
	v_sub_f32_e32 v13, v13, v98
	v_sub_f32_e32 v12, v12, v98
	v_cvt_pk_bf16_f32 v82, v10, v11
	v_max_f32_e32 v10, v3, v3
	v_max_f32_e32 v11, v2, v2
	v_max_f32_e32 v10, v11, v10
	v_max3_f32 v10, v10, v4, v5
	v_max3_f32 v10, v10, v6, v7
	v_max3_f32 v10, v10, v8, v9
	v_max3_f32 v10, v10, v18, v19
	v_max3_f32 v10, v10, v20, v21
	v_max3_f32 v10, v10, v22, v23
	v_max3_f32 v10, v10, v24, v25
	v_mov_b32_e32 v11, v10
	s_nop 1
	v_permlane32_swap_b32_e32 v10, v11
	v_max_f32_e32 v11, v11, v11
	v_max_f32_e32 v10, v10, v10
	v_exp_f32_e32 v16, v16
	v_exp_f32_e32 v17, v17
	v_max_f32_e32 v10, v10, v11
	v_exp_f32_e32 v12, v12
	v_exp_f32_e32 v13, v13
	v_mov_b32_e32 v11, v10
	s_nop 1
	v_permlane16_swap_b32_e32 v10, v11
	v_sub_f32_e32 v33, v33, v98
	v_sub_f32_e32 v32, v32, v98
	v_sub_f32_e32 v15, v15, v98
	v_sub_f32_e32 v14, v14, v98
	v_max_f32_e32 v11, v11, v11
	v_max_f32_e32 v10, v10, v10
	v_sub_f32_e32 v29, v29, v98
	v_sub_f32_e32 v28, v28, v98
	v_exp_f32_e32 v14, v14
	v_exp_f32_e32 v15, v15
	v_cvt_pk_bf16_f32 v81, v16, v17
	v_exp_f32_e32 v16, v32
	v_exp_f32_e32 v17, v33
	v_max_f32_e32 v99, v10, v11
	v_cvt_pk_bf16_f32 v79, v12, v13
	v_exp_f32_e32 v12, v28
	v_exp_f32_e32 v13, v29
	v_sub_f32_e32 v7, v7, v99
	v_sub_f32_e32 v6, v6, v99
	v_exp_f32_e32 v6, v6
	v_exp_f32_e32 v7, v7
	v_sub_f32_e32 v31, v31, v98
	v_sub_f32_e32 v30, v30, v98
	v_exp_f32_e64 v74, -v98
	v_cvt_pk_bf16_f32 v80, v14, v15
	v_exp_f32_e32 v14, v30
	v_exp_f32_e32 v15, v31
	v_cvt_pk_bf16_f32 v85, v16, v17
	v_sub_f32_e32 v17, v18, v99
	v_sub_f32_e32 v9, v9, v99
	v_sub_f32_e32 v8, v8, v99
	v_sub_f32_e32 v5, v5, v99
	v_exp_f32_e64 v18, -v99
	v_sub_f32_e32 v4, v4, v99
	v_sub_f32_e32 v3, v3, v99
	v_sub_f32_e32 v2, v2, v99
	v_cvt_pk_bf16_f32 v83, v12, v13
	v_sub_f32_e32 v10, v25, v99
	v_sub_f32_e32 v11, v24, v99
	v_sub_f32_e32 v12, v23, v99
	v_sub_f32_e32 v13, v22, v99
	v_sub_f32_e32 v16, v19, v99
	v_exp_f32_e32 v2, v2
	v_exp_f32_e32 v3, v3
	v_exp_f32_e32 v4, v4
	v_exp_f32_e32 v5, v5
	v_exp_f32_e32 v8, v8
	v_exp_f32_e32 v9, v9
	v_cvt_pk_bf16_f32 v92, v6, v7
	v_exp_f32_e32 v6, v17
	v_exp_f32_e32 v7, v16
	v_exp_f32_e32 v13, v13
	v_exp_f32_e32 v12, v12
	v_exp_f32_e32 v11, v11
	v_exp_f32_e32 v10, v10
	ds_read_b128 v[34:37], v143 offset:12288
	ds_read_b128 v[38:41], v143 offset:13312
	ds_read_b128 v[66:69], v143 offset:16384
	ds_read_b128 v[70:73], v143 offset:17408
	v_mul_f32_e32 v74, 0, v74
	v_cvt_pk_bf16_f32 v84, v14, v15
	v_sub_f32_e32 v14, v21, v99
	v_sub_f32_e32 v15, v20, v99
	v_mul_f32_e32 v86, 0, v18
	v_mov_b32_e32 v75, v74
	v_mov_b32_e32 v76, v74
	v_mov_b32_e32 v77, v74
	v_mov_b32_e32 v87, v86
	v_mov_b32_e32 v88, v86
	v_mov_b32_e32 v89, v86
	v_cvt_pk_bf16_f32 v90, v2, v3
	v_cvt_pk_bf16_f32 v91, v4, v5
	v_cvt_pk_bf16_f32 v93, v8, v9
	v_exp_f32_e32 v15, v15
	v_exp_f32_e32 v14, v14
	s_waitcnt lgkmcnt(3)
	v_mfma_f32_16x16x32_bf16 v[2:5], v[34:37], v[78:81], v[74:77]
	v_cvt_pk_bf16_f32 v94, v6, v7
	v_cvt_pk_bf16_f32 v96, v13, v12
	v_cvt_pk_bf16_f32 v97, v11, v10
	v_mfma_f32_16x16x32_bf16 v[6:9], v[34:37], v[90:93], v[86:89]
	ds_read_b128 v[10:13], v143 offset:14336
	ds_read_b128 v[18:21], v143 offset:15360
	v_cvt_pk_bf16_f32 v95, v15, v14
	v_pk_add_f32 v[134:135], v[98:99], 0 op_sel_hi:[1,0]
	s_waitcnt lgkmcnt(3)
	v_mfma_f32_16x16x32_bf16 v[26:29], v[66:69], v[82:85], v[2:5]
	v_mfma_f32_16x16x32_bf16 v[30:33], v[66:69], v[94:97], v[6:9]
	v_mfma_f32_16x16x32_bf16 v[2:5], v[38:41], v[78:81], v[74:77]
	v_mfma_f32_16x16x32_bf16 v[6:9], v[38:41], v[90:93], v[86:89]
	ds_read_b128 v[34:37], v143 offset:18432
	ds_read_b128 v[38:41], v143 offset:19456
	s_waitcnt lgkmcnt(3)
	v_mfma_f32_16x16x32_bf16 v[14:17], v[10:13], v[78:81], v[74:77]
	v_mfma_f32_16x16x32_bf16 v[22:25], v[10:13], v[90:93], v[86:89]
	s_waitcnt lgkmcnt(1)
	v_mfma_f32_16x16x32_bf16 v[10:13], v[34:37], v[82:85], v[14:17]
	v_mfma_f32_16x16x32_bf16 v[14:17], v[34:37], v[94:97], v[22:25]
	v_mov_b64_e32 v[34:35], s[80:81]
	v_mov_b64_e32 v[36:37], s[82:83]
	v_mfma_f32_16x16x32_bf16 v[22:25], v[18:21], v[78:81], v[74:77]
	v_mfma_f32_16x16x32_bf16 v[18:21], v[18:21], v[90:93], v[86:89]
	s_waitcnt lgkmcnt(0)
	v_mfma_f32_16x16x32_bf16 v[22:25], v[38:41], v[82:85], v[22:25]
	v_mfma_f32_16x16x32_bf16 v[18:21], v[38:41], v[94:97], v[18:21]
	v_mfma_f32_16x16x32_bf16 v[38:41], v[34:37], v[78:81], v[74:77]
	v_mfma_f32_16x16x32_bf16 v[66:69], v[34:37], v[90:93], v[86:89]
	v_mfma_f32_16x16x32_bf16 v[38:41], v[34:37], v[82:85], v[38:41]
	v_mfma_f32_16x16x32_bf16 v[34:37], v[34:37], v[94:97], v[66:69]
	s_nop 5
	v_mov_b64_e32 v[66:67], s[8:9]
	v_mad_i64_i32 v[136:137], s[4:5], v102, s31, v[66:67]
	s_add_u32 s4, s22, s7
	v_mfma_f32_16x16x32_bf16 v[2:5], v[70:73], v[82:85], v[2:5]
	s_addc_u32 s5, s23, s6
	v_mov_b64_e32 v[66:67], s[4:5]
	s_movk_i32 s4, 0x4200
	v_mfma_f32_16x16x32_bf16 v[6:9], v[70:73], v[94:97], v[6:9]
	v_mad_i64_i32 v[138:139], s[4:5], v101, s4, v[66:67]
	s_mov_b32 s4, 0
	s_mov_b32 s8, 0x41000000
	v_lshl_add_u64 v[136:137], v[136:137], 0, v[0:1]
	v_lshl_add_u64 v[138:139], v[138:139], 0, v[0:1]
	s_mov_b64 s[6:7], 0x134a5000
	v_readfirstlane_b32 s100, v142
	v_lshl_add_u64 v[136:137], v[136:137], 0, s[6:7]
	s_mov_b64 s[6:7], 0x1661c180
	v_xor_b32_e32 v228, 0x80000000, v134
	v_lshl_add_u64 v[138:139], v[138:139], 0, s[6:7]
	v_xor_b32_e32 v232, 0x80000000, v135
	v_mov_b32_e32 v229, v228
	v_mov_b32_e32 v230, v228
	v_mov_b32_e32 v231, v228
	v_mov_b32_e32 v233, v232
	v_mov_b32_e32 v234, v232
	v_mov_b32_e32 v235, v232
	v_mov_b32_e32 v236, s80
	v_mov_b32_e32 v237, s80
	v_mov_b32_e32 v238, s80
	v_mov_b32_e32 v239, s80
	s_branch .LBB0_296
.LBB0_295:
	v_exp_f32_e32 v66, v66
	v_exp_f32_e32 v67, v67
	v_exp_f32_e32 v68, v68
	v_exp_f32_e32 v69, v69
	v_exp_f32_e32 v70, v70
	v_exp_f32_e32 v71, v71
	v_exp_f32_e32 v72, v72
	v_exp_f32_e32 v73, v73
	v_cvt_pk_bf16_f32 v66, v66, v67
	v_cvt_pk_bf16_f32 v67, v68, v69
	v_cvt_pk_bf16_f32 v68, v70, v71
	v_cvt_pk_bf16_f32 v69, v72, v73
	v_exp_f32_e32 v82, v82
	v_exp_f32_e32 v83, v83
	v_exp_f32_e32 v84, v84
	v_exp_f32_e32 v85, v85
	v_exp_f32_e32 v86, v86
	v_exp_f32_e32 v87, v87
	v_exp_f32_e32 v88, v88
	v_exp_f32_e32 v89, v89
	v_exp_f32_e32 v74, v74
	v_exp_f32_e32 v75, v75
	v_exp_f32_e32 v76, v76
	v_exp_f32_e32 v77, v77
	v_exp_f32_e32 v78, v78
	v_exp_f32_e32 v79, v79
	v_exp_f32_e32 v80, v80
	v_exp_f32_e32 v81, v81
	v_cvt_pk_bf16_f32 v82, v82, v83
	v_cvt_pk_bf16_f32 v83, v84, v85
	v_cvt_pk_bf16_f32 v84, v86, v87
	v_cvt_pk_bf16_f32 v85, v88, v89
	v_exp_f32_e32 v86, v118
	v_exp_f32_e32 v87, v119
	v_exp_f32_e32 v88, v120
	v_exp_f32_e32 v89, v121
	v_exp_f32_e32 v118, v122
	v_exp_f32_e32 v119, v123
	v_exp_f32_e32 v120, v124
	v_exp_f32_e32 v121, v125
	v_cvt_pk_bf16_f32 v74, v74, v75
	v_cvt_pk_bf16_f32 v75, v76, v77
	v_cvt_pk_bf16_f32 v76, v78, v79
	v_cvt_pk_bf16_f32 v77, v80, v81
	s_waitcnt lgkmcnt(0)
	v_mfma_f32_16x16x32_bf16 v[26:29], v[98:101], v[82:85], v[26:29]
	v_cvt_pk_bf16_f32 v86, v86, v87
	v_cvt_pk_bf16_f32 v87, v88, v89
	v_cvt_pk_bf16_f32 v88, v118, v119
	v_mfma_f32_16x16x32_bf16 v[30:33], v[98:101], v[74:77], v[30:33]
	v_cvt_pk_bf16_f32 v89, v120, v121
	s_add_i32 s5, s0, 1
	s_cmp_lg_u32 s0, 2
	v_mfma_f32_16x16x32_bf16 v[2:5], v[94:97], v[82:85], v[2:5]
	s_cselect_b32 s0, s5, 0
	s_add_i32 s5, s4, 1
	s_cmp_lg_u32 s4, 2
	v_mfma_f32_16x16x32_bf16 v[6:9], v[94:97], v[74:77], v[6:9]
	s_cselect_b32 s4, s5, 0
	v_lshl_add_u64 v[136:137], v[136:137], 0, s[24:25]
	s_cmp_lg_u32 s2, s1
	v_mfma_f32_16x16x32_bf16 v[10:13], v[110:113], v[82:85], v[10:13]
	v_lshl_add_u64 v[138:139], v[138:139], 0, s[78:79]
	v_mfma_f32_16x16x32_bf16 v[14:17], v[110:113], v[74:77], v[14:17]
	v_mfma_f32_16x16x32_bf16 v[22:25], v[114:117], v[82:85], v[22:25]
	v_mfma_f32_16x16x32_bf16 v[18:21], v[114:117], v[74:77], v[18:21]
	v_mfma_f32_16x16x32_bf16 v[38:41], v[236:239], v[82:85], v[38:41]
	v_mfma_f32_16x16x32_bf16 v[34:37], v[236:239], v[74:77], v[34:37]
	v_mfma_f32_16x16x32_bf16 v[26:29], v[90:93], v[86:89], v[26:29]
	v_mfma_f32_16x16x32_bf16 v[30:33], v[90:93], v[66:69], v[30:33]
	v_mfma_f32_16x16x32_bf16 v[2:5], v[106:109], v[86:89], v[2:5]
	v_mfma_f32_16x16x32_bf16 v[6:9], v[106:109], v[66:69], v[6:9]
	v_mfma_f32_16x16x32_bf16 v[10:13], v[102:105], v[86:89], v[10:13]
	v_mfma_f32_16x16x32_bf16 v[14:17], v[102:105], v[66:69], v[14:17]
	v_mfma_f32_16x16x32_bf16 v[22:25], v[126:129], v[86:89], v[22:25]
	v_mfma_f32_16x16x32_bf16 v[18:21], v[126:129], v[66:69], v[18:21]
	v_mfma_f32_16x16x32_bf16 v[38:41], v[236:239], v[86:89], v[38:41]
	v_mfma_f32_16x16x32_bf16 v[34:37], v[236:239], v[66:69], v[34:37]
	s_cbranch_scc0 .LBB0_302
.LBB0_296:
	s_waitcnt vmcnt(5) lgkmcnt(0)
	s_barrier
	s_mul_i32 s5, s0, 0x5000
	v_add_u32_e32 v144, s5, v143
	ds_read_b128 v[66:69], v144
	ds_read_b128 v[74:77], v144 offset:4096
	ds_read_b128 v[78:81], v144 offset:8192
	ds_read_b128 v[86:89], v144 offset:1024
	ds_read_b128 v[90:93], v144 offset:5120
	ds_read_b128 v[94:97], v144 offset:9216
	ds_read_b128 v[98:101], v144 offset:2048
	ds_read_b128 v[102:105], v144 offset:6144
	ds_read_b128 v[106:109], v144 offset:10240
	ds_read_b128 v[110:113], v144 offset:3072
	ds_read_b128 v[114:117], v144 offset:7168
	ds_read_b128 v[126:129], v144 offset:11264
	s_add_i32 s1, s1, 1
	s_cmp_ge_u32 s1, s2
	s_cbranch_scc1 .LBB0_298
	s_mul_i32 s5, s4, 0x5000
	s_add_i32 s5, s5, s100
	s_mov_b32 m0, s5
	s_add_i32 s6, s5, 0xfc0
	global_load_lds_dwordx4 v[136:137], off
	s_mov_b32 m0, s6
	s_add_i32 s6, s5, 0x1f80
	global_load_lds_dwordx4 v[136:137], off offset:64
	s_mov_b32 m0, s6
	s_add_i32 s6, s5, 0x3000
	global_load_lds_dwordx4 v[136:137], off offset:128
	s_mov_b32 m0, s6
	s_add_i32 s6, s5, 0x3fc0
	global_load_lds_dwordx4 v[138:139], off
	s_mov_b32 m0, s6
	s_nop 0
	global_load_lds_dwordx4 v[138:139], off offset:64
.LBB0_298:
	s_waitcnt lgkmcnt(9)
	v_mfma_f32_16x16x32_bf16 v[82:85], v[66:69], v[46:49], v[228:231]
	v_mfma_f32_16x16x32_bf16 v[66:69], v[66:69], v[62:65], v[232:235]
	v_mfma_f32_16x16x32_bf16 v[66:69], v[74:77], v[58:61], v[66:69]
	v_mfma_f32_16x16x32_bf16 v[82:85], v[74:77], v[42:45], v[82:85]
	v_mfma_f32_16x16x32_bf16 v[74:77], v[78:81], v[54:57], v[66:69]
	s_waitcnt lgkmcnt(6)
	v_mfma_f32_16x16x32_bf16 v[66:69], v[86:89], v[46:49], v[228:231]
	v_mfma_f32_16x16x32_bf16 v[82:85], v[78:81], v[50:53], v[82:85]
	v_mfma_f32_16x16x32_bf16 v[78:81], v[86:89], v[62:65], v[232:235]
	v_mfma_f32_16x16x32_bf16 v[66:69], v[90:93], v[42:45], v[66:69]
	v_mfma_f32_16x16x32_bf16 v[78:81], v[90:93], v[58:61], v[78:81]
	v_mfma_f32_16x16x32_bf16 v[86:89], v[94:97], v[50:53], v[66:69]
	s_waitcnt lgkmcnt(3)
	v_mfma_f32_16x16x32_bf16 v[66:69], v[98:101], v[46:49], v[228:231]
	v_mfma_f32_16x16x32_bf16 v[90:93], v[98:101], v[62:65], v[232:235]
	v_mfma_f32_16x16x32_bf16 v[66:69], v[102:105], v[42:45], v[66:69]
	v_mfma_f32_16x16x32_bf16 v[90:93], v[102:105], v[58:61], v[90:93]
	v_mfma_f32_16x16x32_bf16 v[118:121], v[106:109], v[50:53], v[66:69]
	v_mfma_f32_16x16x32_bf16 v[66:69], v[106:109], v[54:57], v[90:93]
	s_waitcnt lgkmcnt(0)
	v_mfma_f32_16x16x32_bf16 v[90:93], v[110:113], v[46:49], v[228:231]
	v_mfma_f32_16x16x32_bf16 v[70:73], v[110:113], v[62:65], v[232:235]
	v_mfma_f32_16x16x32_bf16 v[90:93], v[114:117], v[42:45], v[90:93]
	v_mfma_f32_16x16x32_bf16 v[70:73], v[114:117], v[58:61], v[70:73]
	v_mfma_f32_16x16x32_bf16 v[78:81], v[94:97], v[54:57], v[78:81]
	v_mfma_f32_16x16x32_bf16 v[122:125], v[126:129], v[50:53], v[90:93]
	v_mfma_f32_16x16x32_bf16 v[70:73], v[126:129], v[54:57], v[70:73]
	ds_read_b128 v[98:101], v144 offset:12288
	s_nop 2
	ds_read_b128 v[90:93], v144 offset:16384
	ds_read_b128 v[94:97], v144 offset:13312
	ds_read_b128 v[106:109], v144 offset:17408
	ds_read_b128 v[110:113], v144 offset:14336
	ds_read_b128 v[102:105], v144 offset:18432
	ds_read_b128 v[114:117], v144 offset:15360
	ds_read_b128 v[126:129], v144 offset:19456
	v_max3_f32 v144, v82, v83, v84
	v_max3_f32 v144, v144, v85, v86
	v_max3_f32 v144, v144, v87, v88
	v_max3_f32 v144, v144, v89, v118
	v_max3_f32 v144, v144, v119, v120
	v_max3_f32 v144, v144, v121, v122
	v_max3_f32 v144, v144, v123, v124
	v_max_f32_e32 v144, v144, v125
	v_cmp_lt_f32_e32 vcc, s8, v144
	s_cbranch_vccz .LBB0_300
	v_mov_b32_e32 v145, v144
	s_nop 1
	v_permlane32_swap_b32_e32 v144, v145
	v_max_f32_e32 v145, v145, v145
	v_max_f32_e32 v144, v144, v144
	v_max_f32_e32 v144, v144, v145
	v_mov_b32_e32 v145, v144
	s_nop 1
	v_permlane16_swap_b32_e32 v144, v145
	v_max_f32_e32 v145, v145, v145
	v_max_f32_e32 v144, v144, v144
	v_max_f32_e32 v144, v144, v145
	v_max_f32_e32 v144, v144, v144
	v_max_f32_e32 v145, 0, v144
	v_exp_f32_e64 v144, -v145
	v_add_f32_e32 v134, v134, v145
	v_sub_f32_e32 v82, v82, v145
	v_sub_f32_e32 v83, v83, v145
	v_pk_mul_f32 v[40:41], v[40:41], v[144:145] op_sel_hi:[1,0]
	v_pk_mul_f32 v[38:39], v[38:39], v[144:145] op_sel_hi:[1,0]
	v_pk_mul_f32 v[28:29], v[28:29], v[144:145] op_sel_hi:[1,0]
	v_pk_mul_f32 v[26:27], v[26:27], v[144:145] op_sel_hi:[1,0]
	v_sub_f32_e32 v84, v84, v145
	v_sub_f32_e32 v85, v85, v145
	v_pk_mul_f32 v[4:5], v[4:5], v[144:145] op_sel_hi:[1,0]
	v_pk_mul_f32 v[2:3], v[2:3], v[144:145] op_sel_hi:[1,0]
	v_sub_f32_e32 v86, v86, v145
	v_sub_f32_e32 v87, v87, v145
	v_sub_f32_e32 v88, v88, v145
	v_sub_f32_e32 v89, v89, v145
	v_pk_mul_f32 v[12:13], v[12:13], v[144:145] op_sel_hi:[1,0]
	v_pk_mul_f32 v[10:11], v[10:11], v[144:145] op_sel_hi:[1,0]
	v_sub_f32_e32 v118, v118, v145
	v_sub_f32_e32 v119, v119, v145
	v_sub_f32_e32 v120, v120, v145
	v_sub_f32_e32 v121, v121, v145
	v_pk_mul_f32 v[24:25], v[24:25], v[144:145] op_sel_hi:[1,0]
	v_pk_mul_f32 v[22:23], v[22:23], v[144:145] op_sel_hi:[1,0]
	v_sub_f32_e32 v122, v122, v145
	v_sub_f32_e32 v123, v123, v145
	v_sub_f32_e32 v124, v124, v145
	v_sub_f32_e32 v125, v125, v145
	v_xor_b32_e32 v228, 0x80000000, v134
	v_mov_b32_e32 v229, v228
	v_mov_b32_e32 v230, v228
	v_mov_b32_e32 v231, v228

.LBB0_348:
	global_load_dwordx4 v[4:7], v[2:3], off offset:-12
	global_load_dwordx4 v[8:11], v[2:3], off offset:4
	global_load_dwordx4 v[12:15], v[2:3], off offset:20
	global_load_dwordx4 v[16:19], v[2:3], off offset:36
	global_load_dwordx4 v[20:23], v[2:3], off offset:52
	global_load_dwordx4 v[24:27], v[2:3], off offset:68
	global_load_dwordx4 v[28:31], v[2:3], off offset:84
	global_load_dwordx4 v[32:35], v[2:3], off offset:100
	s_add_i32 s10, s10, -8
	v_lshl_add_u64 v[2:3], v[2:3], 0, 64
	v_lshl_add_u64 v[2:3], v[2:3], 0, 64
	s_cmp_eq_u32 s10, 0
	s_waitcnt vmcnt(7)
	v_lshlrev_b32_e32 v36, 16, v4
	v_and_b32_e32 v37, 0xffff0000, v4
	v_pk_mul_f32 v[36:37], v[36:37], v[36:37]
	v_and_b32_e32 v39, 0xffff0000, v6
	v_add_f32_e32 v40, v36, v37
	v_and_b32_e32 v38, 0xffff0000, v5
	v_add_f32_e32 v0, v0, v40
	v_lshlrev_b32_e32 v37, 16, v6
	v_lshlrev_b32_e32 v36, 16, v5
	v_pk_mul_f32 v[40:41], v[38:39], v[38:39]
	s_nop 0
	v_pk_fma_f32 v[40:41], v[36:37], v[36:37], v[40:41]
	s_nop 0
	v_add_f32_e32 v0, v0, v40
	v_add_f32_e32 v0, v0, v41
	v_lshlrev_b32_e32 v36, 16, v7
	v_and_b32_e32 v37, 0xffff0000, v7
	v_pk_mul_f32 v[36:37], v[36:37], v[36:37]
	s_nop 0
	v_add_f32_e32 v36, v36, v37
	v_add_f32_e32 v0, v0, v36
	s_waitcnt vmcnt(6)
	v_lshlrev_b32_e32 v36, 16, v8
	v_and_b32_e32 v37, 0xffff0000, v8
	v_pk_mul_f32 v[36:37], v[36:37], v[36:37]
	v_and_b32_e32 v39, 0xffff0000, v10
	v_add_f32_e32 v40, v36, v37
	v_and_b32_e32 v38, 0xffff0000, v9
	v_add_f32_e32 v0, v0, v40
	v_lshlrev_b32_e32 v37, 16, v10
	v_lshlrev_b32_e32 v36, 16, v9
	v_pk_mul_f32 v[40:41], v[38:39], v[38:39]
	s_nop 0
	v_pk_fma_f32 v[40:41], v[36:37], v[36:37], v[40:41]
	s_nop 0
	v_add_f32_e32 v0, v0, v40
	v_add_f32_e32 v0, v0, v41
	v_lshlrev_b32_e32 v36, 16, v11
	v_and_b32_e32 v37, 0xffff0000, v11
	v_pk_mul_f32 v[36:37], v[36:37], v[36:37]
	s_nop 0
	v_add_f32_e32 v36, v36, v37
	v_add_f32_e32 v0, v0, v36
	s_waitcnt vmcnt(5)
	v_lshlrev_b32_e32 v36, 16, v12
	v_and_b32_e32 v37, 0xffff0000, v12
	v_pk_mul_f32 v[36:37], v[36:37], v[36:37]
	v_and_b32_e32 v39, 0xffff0000, v14
	v_add_f32_e32 v40, v36, v37
	v_and_b32_e32 v38, 0xffff0000, v13
	v_add_f32_e32 v0, v0, v40
	v_lshlrev_b32_e32 v37, 16, v14
	v_lshlrev_b32_e32 v36, 16, v13
	v_pk_mul_f32 v[40:41], v[38:39], v[38:39]
	s_nop 0
	v_pk_fma_f32 v[40:41], v[36:37], v[36:37], v[40:41]
	s_nop 0
	v_add_f32_e32 v0, v0, v40
	v_add_f32_e32 v0, v0, v41
	v_lshlrev_b32_e32 v36, 16, v15
	v_and_b32_e32 v37, 0xffff0000, v15
	v_pk_mul_f32 v[36:37], v[36:37], v[36:37]
	s_nop 0
	v_add_f32_e32 v36, v36, v37
	v_add_f32_e32 v0, v0, v36
	s_waitcnt vmcnt(4)
	v_lshlrev_b32_e32 v36, 16, v16
	v_and_b32_e32 v37, 0xffff0000, v16
	v_pk_mul_f32 v[36:37], v[36:37], v[36:37]
	v_and_b32_e32 v39, 0xffff0000, v18
	v_add_f32_e32 v40, v36, v37
	v_and_b32_e32 v38, 0xffff0000, v17
	v_add_f32_e32 v0, v0, v40
	v_lshlrev_b32_e32 v37, 16, v18
	v_lshlrev_b32_e32 v36, 16, v17
	v_pk_mul_f32 v[40:41], v[38:39], v[38:39]
	s_nop 0
	v_pk_fma_f32 v[40:41], v[36:37], v[36:37], v[40:41]
	s_nop 0
	v_add_f32_e32 v0, v0, v40
	v_add_f32_e32 v0, v0, v41
	v_lshlrev_b32_e32 v36, 16, v19
	v_and_b32_e32 v37, 0xffff0000, v19
	v_pk_mul_f32 v[36:37], v[36:37], v[36:37]
	s_nop 0
	v_add_f32_e32 v36, v36, v37
	v_add_f32_e32 v0, v0, v36
	s_waitcnt vmcnt(3)
	v_lshlrev_b32_e32 v36, 16, v20
	v_and_b32_e32 v37, 0xffff0000, v20
	v_pk_mul_f32 v[36:37], v[36:37], v[36:37]
	v_and_b32_e32 v39, 0xffff0000, v22
	v_add_f32_e32 v40, v36, v37
	v_and_b32_e32 v38, 0xffff0000, v21
	v_add_f32_e32 v0, v0, v40
	v_lshlrev_b32_e32 v37, 16, v22
	v_lshlrev_b32_e32 v36, 16, v21
	v_pk_mul_f32 v[40:41], v[38:39], v[38:39]
	s_nop 0
	v_pk_fma_f32 v[40:41], v[36:37], v[36:37], v[40:41]
	s_nop 0
	v_add_f32_e32 v0, v0, v40
	v_add_f32_e32 v0, v0, v41
	v_lshlrev_b32_e32 v36, 16, v23
	v_and_b32_e32 v37, 0xffff0000, v23
	v_pk_mul_f32 v[36:37], v[36:37], v[36:37]
	s_nop 0
	v_add_f32_e32 v36, v36, v37
	v_add_f32_e32 v0, v0, v36
	s_waitcnt vmcnt(2)
	v_lshlrev_b32_e32 v36, 16, v24
	v_and_b32_e32 v37, 0xffff0000, v24
	v_pk_mul_f32 v[36:37], v[36:37], v[36:37]
	v_and_b32_e32 v39, 0xffff0000, v26
	v_add_f32_e32 v40, v36, v37
	v_and_b32_e32 v38, 0xffff0000, v25
	v_add_f32_e32 v0, v0, v40
	v_lshlrev_b32_e32 v37, 16, v26
	v_lshlrev_b32_e32 v36, 16, v25
	v_pk_mul_f32 v[40:41], v[38:39], v[38:39]
	s_nop 0
	v_pk_fma_f32 v[40:41], v[36:37], v[36:37], v[40:41]
	s_nop 0
	v_add_f32_e32 v0, v0, v40
	v_add_f32_e32 v0, v0, v41
	v_lshlrev_b32_e32 v36, 16, v27
	v_and_b32_e32 v37, 0xffff0000, v27
	v_pk_mul_f32 v[36:37], v[36:37], v[36:37]
	s_nop 0
	v_add_f32_e32 v36, v36, v37
	v_add_f32_e32 v0, v0, v36
	s_waitcnt vmcnt(1)
	v_lshlrev_b32_e32 v36, 16, v28
	v_and_b32_e32 v37, 0xffff0000, v28
	v_pk_mul_f32 v[36:37], v[36:37], v[36:37]
	v_and_b32_e32 v39, 0xffff0000, v30
	v_add_f32_e32 v40, v36, v37
	v_and_b32_e32 v38, 0xffff0000, v29
	v_add_f32_e32 v0, v0, v40
	v_lshlrev_b32_e32 v37, 16, v30
	v_lshlrev_b32_e32 v36, 16, v29
	v_pk_mul_f32 v[40:41], v[38:39], v[38:39]
	s_nop 0
	v_pk_fma_f32 v[40:41], v[36:37], v[36:37], v[40:41]
	s_nop 0
	v_add_f32_e32 v0, v0, v40
	v_add_f32_e32 v0, v0, v41
	v_lshlrev_b32_e32 v36, 16, v31
	v_and_b32_e32 v37, 0xffff0000, v31
	v_pk_mul_f32 v[36:37], v[36:37], v[36:37]
	s_nop 0
	v_add_f32_e32 v36, v36, v37
	v_add_f32_e32 v0, v0, v36
	s_waitcnt vmcnt(0)
	v_lshlrev_b32_e32 v36, 16, v32
	v_and_b32_e32 v37, 0xffff0000, v32
	v_pk_mul_f32 v[36:37], v[36:37], v[36:37]
	v_and_b32_e32 v39, 0xffff0000, v34
	v_add_f32_e32 v40, v36, v37
	v_and_b32_e32 v38, 0xffff0000, v33
	v_add_f32_e32 v0, v0, v40
	v_lshlrev_b32_e32 v37, 16, v34
	v_lshlrev_b32_e32 v36, 16, v33
	v_pk_mul_f32 v[40:41], v[38:39], v[38:39]
	s_nop 0
	v_pk_fma_f32 v[40:41], v[36:37], v[36:37], v[40:41]
	s_nop 0
	v_add_f32_e32 v0, v0, v40
	v_add_f32_e32 v0, v0, v41
	v_lshlrev_b32_e32 v36, 16, v35
	v_and_b32_e32 v37, 0xffff0000, v35
	v_pk_mul_f32 v[36:37], v[36:37], v[36:37]
	s_nop 0
	v_add_f32_e32 v36, v36, v37
	v_add_f32_e32 v0, v0, v36
	s_cbranch_scc0 .LBB0_348
	v_xor_b32_e32 v2, 1, v199
	v_cmp_lt_i32_e32 vcc, v2, v200
	s_nop 1
	v_cndmask_b32_e32 v2, v199, v2, vcc
	v_lshlrev_b32_e32 v2, 2, v2
	ds_bpermute_b32 v2, v2, v0
	s_and_saveexec_b64 s[10:11], s[42:43]
	s_cbranch_execz .LBB0_351
	v_cvt_f32_u32_e32 v3, s27
	s_waitcnt lgkmcnt(0)
	v_add_f32_e32 v0, v0, v2
	v_div_scale_f32 v2, s[12:13], v3, v3, v0
	v_rcp_f32_e32 v4, v2
	v_div_scale_f32 v5, vcc, v0, v3, v0
	s_mov_b32 s12, 0x800000
	v_fma_f32 v6, -v2, v4, 1.0
	v_fmac_f32_e32 v4, v6, v4
	v_mul_f32_e32 v6, v5, v4
	v_fma_f32 v7, -v2, v6, v5
	v_fmac_f32_e32 v6, v7, v4
	v_fma_f32 v2, -v2, v6, v5
	v_div_fmas_f32 v2, v2, v4, v6
	v_div_fixup_f32 v0, v2, v3, v0
	v_add_f32_e32 v0, 0x358637bd, v0
	v_mul_f32_e32 v2, 0x4b800000, v0
	v_cmp_gt_f32_e32 vcc, s12, v0
	s_nop 1
	v_cndmask_b32_e32 v0, v0, v2, vcc
	v_rsq_f32_e32 v0, v0
	s_nop 0
	v_mul_f32_e32 v2, 0x45800000, v0
	v_cndmask_b32_e32 v0, v0, v2, vcc
	ds_write_b32 v94, v0

	.amdhsa_kernel _Z4mega6Params
		.amdhsa_group_segment_fixed_size 0
		.amdhsa_private_segment_fixed_size 0
		.amdhsa_kernarg_size 472
		.amdhsa_user_sgpr_count 2
		.amdhsa_user_sgpr_dispatch_ptr 0
		.amdhsa_user_sgpr_queue_ptr 0
		.amdhsa_user_sgpr_kernarg_segment_ptr 1
		.amdhsa_user_sgpr_dispatch_id 0
		.amdhsa_user_sgpr_kernarg_preload_length 0
		.amdhsa_user_sgpr_kernarg_preload_offset 0
		.amdhsa_user_sgpr_private_segment_size 0
		.amdhsa_uses_dynamic_stack 0
		.amdhsa_enable_private_segment 0
		.amdhsa_system_sgpr_workgroup_id_x 1
		.amdhsa_system_sgpr_workgroup_id_y 0
		.amdhsa_system_sgpr_workgroup_id_z 0
		.amdhsa_system_sgpr_workgroup_info 0
		.amdhsa_system_vgpr_workitem_id 2
		.amdhsa_next_free_vgpr 240
		.amdhsa_next_free_sgpr 102
		.amdhsa_accum_offset 240
		.amdhsa_reserve_vcc 1
		.amdhsa_float_round_mode_32 0
		.amdhsa_float_round_mode_16_64 0
		.amdhsa_float_denorm_mode_32 3
		.amdhsa_float_denorm_mode_16_64 3
		.amdhsa_dx10_clamp 1
		.amdhsa_ieee_mode 1
		.amdhsa_fp16_overflow 0
		.amdhsa_tg_split 0
		.amdhsa_exception_fp_ieee_invalid_op 0
		.amdhsa_exception_fp_denorm_src 0
		.amdhsa_exception_fp_ieee_div_zero 0
		.amdhsa_exception_fp_ieee_overflow 0
		.amdhsa_exception_fp_ieee_underflow 0
		.amdhsa_exception_fp_ieee_inexact 0
		.amdhsa_exception_int_div_zero 0
	.end_amdhsa_kernel

amdhsa.kernels:
  - .agpr_count:     0
    .args:
      - .offset:         0
        .size:           216
        .value_kind:     by_value
      - .offset:         216
        .size:           4
        .value_kind:     hidden_block_count_x
      - .offset:         220
        .size:           4
        .value_kind:     hidden_block_count_y
      - .offset:         224
        .size:           4
        .value_kind:     hidden_block_count_z
      - .offset:         228
        .size:           2
        .value_kind:     hidden_group_size_x
      - .offset:         230
        .size:           2
        .value_kind:     hidden_group_size_y
      - .offset:         232
        .size:           2
        .value_kind:     hidden_group_size_z
      - .offset:         234
        .size:           2
        .value_kind:     hidden_remainder_x
      - .offset:         236
        .size:           2
        .value_kind:     hidden_remainder_y
      - .offset:         238
        .size:           2
        .value_kind:     hidden_remainder_z
      - .offset:         256
        .size:           8
        .value_kind:     hidden_global_offset_x
      - .offset:         264
        .size:           8
        .value_kind:     hidden_global_offset_y
      - .offset:         272
        .size:           8
        .value_kind:     hidden_global_offset_z
      - .offset:         280
        .size:           2
        .value_kind:     hidden_grid_dims
      - .offset:         304
        .size:           8
        .value_kind:     hidden_multigrid_sync_arg
      - .offset:         336
        .size:           4
        .value_kind:     hidden_dynamic_lds_size
    .group_segment_fixed_size: 0
    .kernarg_segment_align: 8
    .kernarg_segment_size: 472
    .language:       OpenCL C
    .language_version:
      - 2
      - 0
    .max_flat_workgroup_size: 256
    .name:           _Z4mega6Params
    .private_segment_fixed_size: 0
    .sgpr_count:     108
    .sgpr_spill_count: 249
    .symbol:         _Z4mega6Params.kd
    .uniform_work_group_size: 1
    .uses_dynamic_stack: false
    .vgpr_count:     240
    .vgpr_spill_count: 0
    .wavefront_size: 64
